# memory-bound phases P2,P6,P9,P13 store write-through (sc1) and the barrier after them drops buffer_wbl2
# speedup vs baseline: 1.0166x; 1.0011x over previous
.LBB0_480:
	s_or_b64 exec, exec, s[18:19]
	v_mov_b32_e32 v34, s0
	v_mov_b32_e32 v35, s1
	v_lshlrev_b64 v[110:111], 1, v[32:33]
	v_readfirstlane_b32 s16, v34
	v_readfirstlane_b32 s17, v35
	s_load_dwordx2 s[16:17], s[16:17], 0xc0
	v_or_b32_e32 v150, 1, v149
	v_or_b32_e32 v148, 2, v149
	v_or_b32_e32 v147, 3, v149
	v_or_b32_e32 v146, 4, v149
	s_waitcnt lgkmcnt(0)
	v_mov_b64_e32 v[34:35], s[16:17]
	v_mad_i64_i32 v[34:35], s[16:17], v149, s24, v[34:35]
	v_lshl_add_u64 v[32:33], v[34:35], 0, v[110:111]
	v_add_co_u32_e32 v32, vcc, s25, v32
	v_or_b32_e32 v145, 5, v149
	s_nop 0
	v_addc_co_u32_e32 v33, vcc, 0, v33, vcc
	global_load_dwordx4 v[104:107], v[32:33], off
	v_mov_b32_e32 v32, s0
	v_mov_b32_e32 v33, s1
	v_or_b32_e32 v144, 6, v149
	v_readfirstlane_b32 s16, v32
	v_readfirstlane_b32 s17, v33
	s_load_dwordx2 s[16:17], s[16:17], 0xc0
	v_or_b32_e32 v143, 7, v149
	v_or_b32_e32 v142, 8, v149
	v_or_b32_e32 v141, 9, v149
	v_or_b32_e32 v140, 10, v149
	s_waitcnt lgkmcnt(0)
	v_mov_b64_e32 v[32:33], s[16:17]
	v_mad_i64_i32 v[32:33], s[16:17], v150, s24, v[32:33]
	v_lshl_add_u64 v[32:33], v[32:33], 0, v[110:111]
	v_add_co_u32_e32 v32, vcc, s25, v32
	s_waitcnt vmcnt(1)
	v_lshlrev_b32_e32 v117, 16, v28
	v_addc_co_u32_e32 v33, vcc, 0, v33, vcc
	global_load_dwordx4 v[84:87], v[32:33], off
	v_mov_b32_e32 v32, s0
	v_mov_b32_e32 v33, s1
	v_and_b32_e32 v125, 0xffff0000, v28
	v_readfirstlane_b32 s16, v32
	v_readfirstlane_b32 s17, v33
	s_load_dwordx2 s[16:17], s[16:17], 0xc0
	v_lshlrev_b32_e32 v121, 16, v29
	v_and_b32_e32 v119, 0xffff0000, v29
	v_or_b32_e32 v139, 11, v149
	v_lshlrev_b32_e32 v116, 16, v24
	s_waitcnt lgkmcnt(0)
	v_mov_b64_e32 v[32:33], s[16:17]
	v_mad_i64_i32 v[32:33], s[16:17], v148, s24, v[32:33]
	v_lshl_add_u64 v[32:33], v[32:33], 0, v[110:111]
	v_add_co_u32_e32 v32, vcc, s25, v32
	v_mov_b32_e32 v112, v96
	s_nop 0
	v_addc_co_u32_e32 v33, vcc, 0, v33, vcc
	global_load_dwordx4 v[88:91], v[32:33], off
	v_mov_b32_e32 v32, s0
	v_mov_b32_e32 v33, s1
	v_mov_b32_e32 v113, v12
	v_readfirstlane_b32 s16, v32
	v_readfirstlane_b32 s17, v33
	s_load_dwordx2 s[16:17], s[16:17], 0xc0
	v_pk_mul_f32 v[114:115], v[112:113], v[116:117]
	v_lshlrev_b32_e32 v152, 16, v100
	v_add_f32_e32 v12, v20, v114
	v_add_f32_e32 v12, v12, v115
	s_waitcnt lgkmcnt(0)
	v_mov_b64_e32 v[32:33], s[16:17]
	v_mad_i64_i32 v[32:33], s[16:17], v147, s24, v[32:33]
	v_lshl_add_u64 v[32:33], v[32:33], 0, v[110:111]
	v_add_co_u32_e32 v32, vcc, s25, v32
	v_mov_b32_e32 v114, v92
	s_nop 0
	v_addc_co_u32_e32 v33, vcc, 0, v33, vcc
	global_load_dwordx4 v[68:71], v[32:33], off
	v_mov_b32_e32 v32, s0
	v_mov_b32_e32 v33, s1
	v_mov_b32_e32 v115, v16
	v_readfirstlane_b32 s16, v32
	v_readfirstlane_b32 s17, v33
	s_load_dwordx2 s[16:17], s[16:17], 0xc0
	v_and_b32_e32 v124, 0xffff0000, v24
	v_or_b32_e32 v138, 12, v149
	v_lshlrev_b32_e32 v120, 16, v25
	v_lshlrev_b32_e32 v156, 16, v101
	s_waitcnt lgkmcnt(0)
	v_mov_b64_e32 v[32:33], s[16:17]
	v_mad_i64_i32 v[32:33], s[16:17], v146, s24, v[32:33]
	v_lshl_add_u64 v[32:33], v[32:33], 0, v[110:111]
	v_add_co_u32_e32 v32, vcc, s25, v32
	s_waitcnt vmcnt(3)
	v_lshlrev_b32_e32 v153, 16, v104
	v_addc_co_u32_e32 v33, vcc, 0, v33, vcc
	global_load_dwordx4 v[72:75], v[32:33], off
	v_mov_b32_e32 v32, s0
	v_mov_b32_e32 v33, s1
	v_pk_mul_f32 v[154:155], v[114:115], v[152:153]
	v_readfirstlane_b32 s16, v32
	v_readfirstlane_b32 s17, v33
	s_load_dwordx2 s[16:17], s[16:17], 0xc0
	v_add_f32_e32 v12, v12, v154
	v_add_f32_e32 v116, v12, v155
	v_mov_b32_e32 v12, v97
	v_pk_mul_f32 v[96:97], v[12:13], v[124:125]
	s_waitcnt lgkmcnt(0)
	v_mov_b64_e32 v[32:33], s[16:17]
	v_mad_i64_i32 v[32:33], s[16:17], v145, s24, v[32:33]
	v_lshl_add_u64 v[32:33], v[32:33], 0, v[110:111]
	v_add_co_u32_e32 v32, vcc, s25, v32
	v_add_f32_e32 v16, v21, v96
	s_nop 0
	v_addc_co_u32_e32 v33, vcc, 0, v33, vcc
	global_load_dwordx4 v[60:63], v[32:33], off
	v_mov_b32_e32 v32, s0
	v_mov_b32_e32 v33, s1
	v_add_f32_e32 v96, v16, v97
	v_readfirstlane_b32 s16, v32
	v_readfirstlane_b32 s17, v33
	s_load_dwordx2 s[16:17], s[16:17], 0xc0
	v_and_b32_e32 v155, 0xffff0000, v104
	v_and_b32_e32 v154, 0xffff0000, v100
	v_mov_b32_e32 v16, v93
	v_pk_mul_f32 v[92:93], v[16:17], v[154:155]
	s_waitcnt lgkmcnt(0)
	v_mov_b64_e32 v[32:33], s[16:17]
	v_mad_i64_i32 v[32:33], s[16:17], v144, s24, v[32:33]
	v_lshl_add_u64 v[32:33], v[32:33], 0, v[110:111]
	v_add_co_u32_e32 v32, vcc, s25, v32
	v_add_f32_e32 v92, v96, v92
	s_nop 0
	v_addc_co_u32_e32 v33, vcc, 0, v33, vcc
	global_load_dwordx4 v[64:67], v[32:33], off
	v_mov_b32_e32 v32, s0
	v_mov_b32_e32 v33, s1
	v_add_f32_e32 v124, v92, v93
	v_readfirstlane_b32 s16, v32
	v_readfirstlane_b32 s17, v33
	s_load_dwordx2 s[16:17], s[16:17], 0xc0
	v_mov_b32_e32 v92, v98
	v_mov_b32_e32 v93, v14
	v_pk_mul_f32 v[96:97], v[92:93], v[120:121]
	v_lshlrev_b32_e32 v157, 16, v105
	s_waitcnt lgkmcnt(0)
	v_mov_b64_e32 v[32:33], s[16:17]
	v_mad_i64_i32 v[32:33], s[16:17], v143, s24, v[32:33]
	v_lshl_add_u64 v[32:33], v[32:33], 0, v[110:111]
	v_add_co_u32_e32 v32, vcc, s25, v32
	v_add_f32_e32 v14, v22, v96
	s_nop 0
	v_addc_co_u32_e32 v33, vcc, 0, v33, vcc
	global_load_dwordx4 v[52:55], v[32:33], off
	v_mov_b32_e32 v32, s0
	v_mov_b32_e32 v33, s1
	v_add_f32_e32 v14, v14, v97
	v_readfirstlane_b32 s16, v32
	v_readfirstlane_b32 s17, v33
	s_load_dwordx2 s[16:17], s[16:17], 0xc0
	v_mov_b32_e32 v96, v94
	v_mov_b32_e32 v97, v18
	v_pk_mul_f32 v[158:159], v[96:97], v[156:157]
	v_and_b32_e32 v118, 0xffff0000, v25
	s_waitcnt lgkmcnt(0)
	v_mov_b64_e32 v[32:33], s[16:17]
	v_mad_i64_i32 v[32:33], s[16:17], v142, s24, v[32:33]
	v_lshl_add_u64 v[32:33], v[32:33], 0, v[110:111]
	v_add_co_u32_e32 v32, vcc, s25, v32
	v_add_f32_e32 v14, v14, v158
	s_nop 0
	v_addc_co_u32_e32 v33, vcc, 0, v33, vcc
	global_load_dwordx4 v[56:59], v[32:33], off
	v_mov_b32_e32 v32, s0
	v_mov_b32_e32 v33, s1
	v_add_f32_e32 v120, v14, v159
	v_readfirstlane_b32 s16, v32
	v_readfirstlane_b32 s17, v33
	s_load_dwordx2 s[16:17], s[16:17], 0xc0
	v_mov_b32_e32 v14, v99
	v_pk_mul_f32 v[98:99], v[14:15], v[118:119]
	v_or_b32_e32 v137, 13, v149
	v_add_f32_e32 v18, v23, v98
	s_waitcnt lgkmcnt(0)
	v_mov_b64_e32 v[32:33], s[16:17]
	v_mad_i64_i32 v[32:33], s[16:17], v141, s24, v[32:33]
	v_lshl_add_u64 v[32:33], v[32:33], 0, v[110:111]
	v_add_co_u32_e32 v32, vcc, s25, v32
	v_add_f32_e32 v98, v18, v99
	s_nop 0
	v_addc_co_u32_e32 v33, vcc, 0, v33, vcc
	global_load_dwordx4 v[44:47], v[32:33], off
	v_mov_b32_e32 v32, s0
	v_mov_b32_e32 v33, s1
	v_and_b32_e32 v105, 0xffff0000, v105
	v_readfirstlane_b32 s16, v32
	v_readfirstlane_b32 s17, v33
	s_load_dwordx2 s[16:17], s[16:17], 0xc0
	v_and_b32_e32 v104, 0xffff0000, v101
	v_mov_b32_e32 v18, v95
	v_pk_mul_f32 v[94:95], v[18:19], v[104:105]
	v_lshlrev_b32_e32 v129, 16, v30
	s_waitcnt lgkmcnt(0)
	v_mov_b64_e32 v[32:33], s[16:17]
	v_mad_i64_i32 v[32:33], s[16:17], v140, s24, v[32:33]
	v_lshl_add_u64 v[32:33], v[32:33], 0, v[110:111]
	v_add_co_u32_e32 v32, vcc, s25, v32
	v_add_f32_e32 v94, v98, v94
	s_nop 0
	v_addc_co_u32_e32 v33, vcc, 0, v33, vcc
	global_load_dwordx4 v[48:51], v[32:33], off
	v_mov_b32_e32 v32, s0
	v_mov_b32_e32 v33, s1
	v_lshlrev_b32_e32 v128, 16, v26
	v_readfirstlane_b32 s16, v32
	v_readfirstlane_b32 s17, v33
	s_load_dwordx2 s[16:17], s[16:17], 0xc0
	v_add_f32_e32 v118, v94, v95
	v_mov_b32_e32 v94, v80
	v_mov_b32_e32 v95, v0
	v_mov_b32_e32 v24, s0
	s_waitcnt lgkmcnt(0)
	v_mov_b64_e32 v[28:29], s[16:17]
	v_mad_i64_i32 v[28:29], s[16:17], v139, s24, v[28:29]
	v_lshl_add_u64 v[28:29], v[28:29], 0, v[110:111]
	v_add_co_u32_e32 v28, vcc, s25, v28
	v_mov_b32_e32 v32, s1
	s_nop 0
	v_addc_co_u32_e32 v29, vcc, 0, v29, vcc
	global_load_dwordx4 v[36:39], v[28:29], off
	v_mov_b32_e32 v28, s0
	v_mov_b32_e32 v29, s1
	v_pk_mul_f32 v[98:99], v[94:95], v[128:129]
	v_readfirstlane_b32 s16, v28
	v_readfirstlane_b32 s17, v29
	s_load_dwordx2 s[16:17], s[16:17], 0xc0
	v_and_b32_e32 v127, 0xffff0000, v30
	v_lshlrev_b32_e32 v123, 16, v31
	v_and_b32_e32 v131, 0xffff0000, v31
	v_add_f32_e32 v0, v8, v98
	s_waitcnt lgkmcnt(0)
	v_mov_b64_e32 v[28:29], s[16:17]
	v_mad_i64_i32 v[28:29], s[16:17], v138, s24, v[28:29]
	v_lshl_add_u64 v[28:29], v[28:29], 0, v[110:111]
	v_add_co_u32_e32 v28, vcc, s25, v28
	v_add_f32_e32 v0, v0, v99
	s_nop 0
	v_addc_co_u32_e32 v29, vcc, 0, v29, vcc
	global_load_dwordx4 v[40:43], v[28:29], off
	v_mov_b32_e32 v28, s0
	v_mov_b32_e32 v29, s1
	v_lshlrev_b32_e32 v159, 16, v106
	v_readfirstlane_b32 s16, v28
	v_readfirstlane_b32 s17, v29
	s_load_dwordx2 s[16:17], s[16:17], 0xc0
	v_lshlrev_b32_e32 v158, 16, v102
	v_mov_b32_e32 v98, v76
	v_mov_b32_e32 v99, v4
	v_pk_mul_f32 v[100:101], v[98:99], v[158:159]
	s_waitcnt lgkmcnt(0)
	v_mov_b64_e32 v[28:29], s[16:17]
	v_mad_i64_i32 v[28:29], s[16:17], v137, s24, v[28:29]
	v_lshl_add_u64 v[28:29], v[28:29], 0, v[110:111]
	v_add_co_u32_e32 v28, vcc, s25, v28
	v_add_f32_e32 v0, v0, v100
	s_nop 0
	v_addc_co_u32_e32 v29, vcc, 0, v29, vcc
	global_load_dwordx4 v[28:31], v[28:29], off
	v_and_b32_e32 v126, 0xffff0000, v26
	v_readfirstlane_b32 s16, v24
	v_readfirstlane_b32 s17, v32
	s_load_dwordx2 s[16:17], s[16:17], 0xc0
	v_add_f32_e32 v128, v0, v101
	v_mov_b32_e32 v0, v81
	v_pk_mul_f32 v[80:81], v[0:1], v[126:127]
	v_or_b32_e32 v136, 14, v149
	s_waitcnt lgkmcnt(0)
	v_mov_b64_e32 v[24:25], s[16:17]
	v_add_f32_e32 v4, v9, v80
	v_mad_i64_i32 v[24:25], s[16:17], v136, s24, v[24:25]
	v_add_f32_e32 v80, v4, v81
	v_and_b32_e32 v161, 0xffff0000, v106
	v_and_b32_e32 v160, 0xffff0000, v102
	v_mov_b32_e32 v4, v77
	v_lshl_add_u64 v[24:25], v[24:25], 0, v[110:111]
	v_pk_mul_f32 v[76:77], v[4:5], v[160:161]
	v_add_co_u32_e32 v24, vcc, s25, v24
	v_add_f32_e32 v76, v80, v76
	s_nop 0
	v_addc_co_u32_e32 v25, vcc, 0, v25, vcc
	v_lshlrev_b32_e32 v122, 16, v27
	v_add_f32_e32 v102, v76, v77
	v_mov_b32_e32 v76, v82
	v_mov_b32_e32 v77, v2
	global_load_dwordx4 v[32:35], v[24:25], off
	v_mov_b32_e32 v24, s0
	v_mov_b32_e32 v25, s1
	v_pk_mul_f32 v[80:81], v[76:77], v[122:123]
	v_lshlrev_b32_e32 v162, 16, v103
	v_readfirstlane_b32 s16, v24
	v_readfirstlane_b32 s17, v25
	v_add_f32_e32 v2, v10, v80
	s_load_dwordx2 s[16:17], s[16:17], 0xc0
	v_add_f32_e32 v2, v2, v81
	v_lshlrev_b32_e32 v163, 16, v107
	v_mov_b32_e32 v80, v78
	v_mov_b32_e32 v81, v6
	v_pk_mul_f32 v[100:101], v[80:81], v[162:163]
	v_and_b32_e32 v130, 0xffff0000, v27
	v_add_f32_e32 v2, v2, v100
	v_add_f32_e32 v122, v2, v101
	v_mov_b32_e32 v2, v83
	v_pk_mul_f32 v[82:83], v[2:3], v[130:131]
	v_or_b32_e32 v135, 15, v149
	s_waitcnt lgkmcnt(0)
	v_mov_b64_e32 v[24:25], s[16:17]
	v_add_f32_e32 v6, v11, v82
	v_mad_i64_i32 v[24:25], s[16:17], v135, s24, v[24:25]
	v_add_f32_e32 v82, v6, v83
	v_and_b32_e32 v107, 0xffff0000, v107
	v_and_b32_e32 v106, 0xffff0000, v103
	v_mov_b32_e32 v6, v79
	v_lshl_add_u64 v[24:25], v[24:25], 0, v[110:111]
	v_pk_mul_f32 v[78:79], v[6:7], v[106:107]
	v_add_co_u32_e32 v24, vcc, s25, v24
	v_add_f32_e32 v78, v82, v78
	s_nop 0
	v_addc_co_u32_e32 v25, vcc, 0, v25, vcc
	v_add_f32_e32 v78, v78, v79
	global_load_dwordx4 v[24:27], v[24:25], off
	v_cvt_pk_bf16_f32 v100, v116, v124
	v_cvt_pk_bf16_f32 v101, v120, v118
	v_cvt_pk_bf16_f32 v102, v128, v102
	v_cvt_pk_bf16_f32 v103, v122, v78
	v_mov_b32_e32 v78, s0
	v_mov_b32_e32 v79, s1
	v_mov_b32_e32 v133, s0
	v_readfirstlane_b32 s16, v78
	v_readfirstlane_b32 s17, v79
	s_load_dwordx2 s[16:17], s[16:17], 0xc0
	v_mov_b32_e32 v134, s1
	v_add_u32_e32 v109, s3, v109
	v_add_u32_e32 v108, s20, v108
	v_and_b32_e32 v242, s99, v254
	v_lshl_or_b32 v109, v242, 12, v109
	s_waitcnt lgkmcnt(0)
	v_mov_b64_e32 v[78:79], s[16:17]
	v_mad_i64_i32 v[78:79], s[16:17], v149, s24, v[78:79]
	v_lshl_add_u64 v[78:79], v[78:79], 0, v[110:111]
	v_add_co_u32_e32 v78, vcc, s26, v78
	s_nop 1
	v_addc_co_u32_e32 v79, vcc, 0, v79, vcc
	global_store_dwordx4 v[78:79], v[100:103], off sc1
	v_mov_b32_e32 v78, v117
	v_mov_b32_e32 v79, v152
	v_pk_mul_f32 v[78:79], v[112:113], v[78:79]
	s_nop 0
	v_add_f32_e32 v78, v20, v78
	v_add_f32_e32 v102, v78, v79
	v_mov_b32_e32 v78, v125
	v_mov_b32_e32 v79, v154
	v_pk_mul_f32 v[78:79], v[12:13], v[78:79]
	s_nop 0
	v_add_f32_e32 v78, v21, v78
	v_add_f32_e32 v118, v78, v79
	v_mov_b32_e32 v78, v121
	v_mov_b32_e32 v79, v156
	v_pk_mul_f32 v[78:79], v[92:93], v[78:79]
	s_nop 0
	v_add_f32_e32 v78, v22, v78
	v_add_f32_e32 v124, v78, v79
	v_mov_b32_e32 v78, v119
	v_mov_b32_e32 v79, v104
	v_pk_mul_f32 v[78:79], v[14:15], v[78:79]
	s_nop 0
	v_add_f32_e32 v78, v23, v78
	v_add_f32_e32 v125, v78, v79
	v_mov_b32_e32 v78, v129
	v_mov_b32_e32 v79, v158
	v_pk_mul_f32 v[78:79], v[94:95], v[78:79]
	s_nop 0
	v_add_f32_e32 v78, v8, v78
	v_add_f32_e32 v126, v78, v79
	v_mov_b32_e32 v78, v127
	v_mov_b32_e32 v79, v160
	v_pk_mul_f32 v[78:79], v[0:1], v[78:79]
	s_nop 0
	v_add_f32_e32 v78, v9, v78
	v_add_f32_e32 v130, v78, v79
	v_mov_b32_e32 v78, v123
	v_mov_b32_e32 v79, v162
	v_pk_mul_f32 v[78:79], v[76:77], v[78:79]
	s_nop 0
	v_add_f32_e32 v78, v10, v78
	v_add_f32_e32 v149, v78, v79
	v_mov_b32_e32 v78, v131
	v_mov_b32_e32 v79, v106
	v_pk_mul_f32 v[78:79], v[2:3], v[78:79]
	s_nop 0
	v_add_f32_e32 v78, v11, v78
	v_add_f32_e32 v151, v78, v79
	v_pk_mul_f32 v[78:79], v[112:113], v[152:153]
	s_nop 0
	v_add_f32_e32 v78, v20, v78
	v_add_f32_e32 v103, v78, v79
	s_waitcnt vmcnt(15)
	v_lshlrev_b32_e32 v78, 16, v84
	s_waitcnt vmcnt(14)
	v_lshlrev_b32_e32 v79, 16, v88
	v_pk_mov_b32 v[100:101], v[152:153], v[78:79] op_sel:[1,0]
	s_nop 0
	v_pk_mul_f32 v[82:83], v[114:115], v[100:101]
	s_nop 0
	v_add_f32_e32 v82, v102, v82
	v_add_f32_e32 v119, v82, v83
	v_pk_mul_f32 v[82:83], v[114:115], v[78:79]
	v_and_b32_e32 v102, 0xffff0000, v84
	v_add_f32_e32 v82, v103, v82
	v_add_f32_e32 v164, v82, v83
	v_pk_mul_f32 v[82:83], v[12:13], v[154:155]
	v_and_b32_e32 v103, 0xffff0000, v88
	v_add_f32_e32 v82, v21, v82
	v_pk_mov_b32 v[116:117], v[154:155], v[102:103] op_sel:[1,0]
	v_add_f32_e32 v120, v82, v83
	v_pk_mul_f32 v[82:83], v[16:17], v[116:117]
	v_and_b32_e32 v88, 0xffff0000, v85
	v_add_f32_e32 v82, v118, v82
	v_add_f32_e32 v82, v82, v83
	v_cvt_pk_bf16_f32 v82, v119, v82
	v_pk_mul_f32 v[118:119], v[16:17], v[102:103]
	s_nop 0
	v_add_f32_e32 v83, v120, v118
	v_add_f32_e32 v165, v83, v119
	v_pk_mul_f32 v[118:119], v[92:93], v[156:157]
	s_nop 0
	v_add_f32_e32 v83, v22, v118
	v_add_f32_e32 v83, v83, v119
	v_lshlrev_b32_e32 v118, 16, v85
	v_lshlrev_b32_e32 v119, 16, v89
	v_pk_mov_b32 v[120:121], v[156:157], v[118:119] op_sel:[1,0]
	v_and_b32_e32 v89, 0xffff0000, v89
	v_pk_mul_f32 v[122:123], v[96:97], v[120:121]
	s_nop 0
	v_add_f32_e32 v84, v124, v122
	v_add_f32_e32 v124, v84, v123
	v_pk_mul_f32 v[122:123], v[96:97], v[118:119]
	s_nop 0
	v_add_f32_e32 v83, v83, v122
	v_add_f32_e32 v166, v83, v123
	v_pk_mul_f32 v[122:123], v[14:15], v[104:105]
	v_pk_mov_b32 v[104:105], v[104:105], v[88:89] op_sel:[1,0]
	v_add_f32_e32 v83, v23, v122
	v_pk_mul_f32 v[84:85], v[18:19], v[104:105]
	v_add_f32_e32 v122, v83, v123
	v_add_f32_e32 v83, v125, v84
	v_add_f32_e32 v83, v83, v85
	v_pk_mul_f32 v[84:85], v[18:19], v[88:89]
	v_lshlrev_b32_e32 v123, 16, v90
	v_add_f32_e32 v84, v122, v84
	v_add_f32_e32 v167, v84, v85
	v_pk_mul_f32 v[84:85], v[94:95], v[158:159]
	v_lshlrev_b32_e32 v122, 16, v86
	v_cvt_pk_bf16_f32 v83, v124, v83
	v_add_f32_e32 v84, v8, v84
	v_pk_mov_b32 v[124:125], v[158:159], v[122:123] op_sel:[1,0]
	v_add_f32_e32 v127, v84, v85
	v_pk_mul_f32 v[84:85], v[98:99], v[124:125]
	s_nop 0
	v_add_f32_e32 v84, v126, v84
	v_add_f32_e32 v131, v84, v85
	v_pk_mul_f32 v[84:85], v[98:99], v[122:123]
	v_and_b32_e32 v126, 0xffff0000, v86
	v_add_f32_e32 v84, v127, v84
	v_add_f32_e32 v158, v84, v85
	v_pk_mul_f32 v[84:85], v[0:1], v[160:161]
	v_and_b32_e32 v127, 0xffff0000, v90
	v_add_f32_e32 v84, v9, v84
	v_pk_mov_b32 v[128:129], v[160:161], v[126:127] op_sel:[1,0]
	v_add_f32_e32 v152, v84, v85
	v_pk_mul_f32 v[84:85], v[4:5], v[128:129]
	v_and_b32_e32 v90, 0xffff0000, v87
	v_add_f32_e32 v84, v130, v84
	v_add_f32_e32 v84, v84, v85
	v_cvt_pk_bf16_f32 v84, v131, v84
	v_pk_mul_f32 v[130:131], v[4:5], v[126:127]
	s_nop 0
	v_add_f32_e32 v85, v152, v130
	v_add_f32_e32 v159, v85, v131
	v_pk_mul_f32 v[130:131], v[76:77], v[162:163]
	s_nop 0
	v_add_f32_e32 v85, v10, v130
	v_add_f32_e32 v85, v85, v131
	v_lshlrev_b32_e32 v130, 16, v87
	v_lshlrev_b32_e32 v131, 16, v91
	v_pk_mov_b32 v[152:153], v[162:163], v[130:131] op_sel:[1,0]
	v_and_b32_e32 v91, 0xffff0000, v91
	v_pk_mul_f32 v[154:155], v[80:81], v[152:153]
	s_nop 0
	v_add_f32_e32 v86, v149, v154
	v_add_f32_e32 v149, v86, v155
	v_pk_mov_b32 v[86:87], v[106:107], v[90:91] op_sel:[1,0]
	v_pk_mul_f32 v[154:155], v[80:81], v[130:131]
	v_pk_mul_f32 v[156:157], v[6:7], v[86:87]
	v_add_f32_e32 v154, v85, v154
	v_add_f32_e32 v85, v151, v156
	v_add_f32_e32 v85, v85, v157
	v_cvt_pk_bf16_f32 v85, v149, v85
	v_mov_b32_e32 v149, s0
	v_mov_b32_e32 v151, s1
	v_pk_mul_f32 v[106:107], v[2:3], v[106:107]
	v_readfirstlane_b32 s16, v149
	v_readfirstlane_b32 s17, v151
	s_load_dwordx2 s[16:17], s[16:17], 0xc0
	v_add_f32_e32 v106, v11, v106
	v_add_f32_e32 v151, v106, v107
	v_add_f32_e32 v149, v154, v155
	s_waitcnt lgkmcnt(0)
	v_mov_b64_e32 v[106:107], s[16:17]
	v_mad_i64_i32 v[106:107], s[16:17], v150, s24, v[106:107]
	v_lshl_add_u64 v[106:107], v[106:107], 0, v[110:111]
	v_add_co_u32_e32 v106, vcc, s26, v106
	s_nop 1
	v_addc_co_u32_e32 v107, vcc, 0, v107, vcc
	global_store_dwordx4 v[106:107], v[82:85], off sc1
	v_mov_b32_e32 v106, s0
	v_mov_b32_e32 v107, s1
	v_pk_mul_f32 v[82:83], v[6:7], v[90:91]
	s_nop 0
	v_add_f32_e32 v82, v151, v82
	v_add_f32_e32 v85, v82, v83
	v_cvt_pk_bf16_f32 v82, v164, v165
	v_cvt_pk_bf16_f32 v83, v166, v167
	v_cvt_pk_bf16_f32 v84, v158, v159
	v_cvt_pk_bf16_f32 v85, v149, v85
	s_nop 0
	v_readfirstlane_b32 s16, v106
	v_readfirstlane_b32 s17, v107
	s_load_dwordx2 s[16:17], s[16:17], 0xc0
	s_waitcnt lgkmcnt(0)
	v_mov_b64_e32 v[106:107], s[16:17]
	v_mad_i64_i32 v[106:107], s[16:17], v148, s24, v[106:107]
	v_lshl_add_u64 v[106:107], v[106:107], 0, v[110:111]
	v_add_co_u32_e32 v106, vcc, s26, v106
	s_nop 1
	v_addc_co_u32_e32 v107, vcc, 0, v107, vcc
	global_store_dwordx4 v[106:107], v[82:85], off sc1
	s_nop 1
	v_pk_mul_f32 v[82:83], v[112:113], v[100:101]
	s_nop 0
	v_add_f32_e32 v82, v20, v82
	v_add_f32_e32 v100, v82, v83
	v_pk_mul_f32 v[82:83], v[12:13], v[116:117]
	s_nop 0
	v_add_f32_e32 v82, v21, v82
	v_add_f32_e32 v106, v82, v83
	v_pk_mul_f32 v[82:83], v[92:93], v[120:121]
	s_nop 0
	v_add_f32_e32 v82, v22, v82
	v_add_f32_e32 v107, v82, v83
	v_pk_mul_f32 v[82:83], v[14:15], v[104:105]
	s_nop 0
	v_add_f32_e32 v82, v23, v82
	v_add_f32_e32 v116, v82, v83
	v_pk_mul_f32 v[82:83], v[94:95], v[124:125]
	s_nop 0
	v_add_f32_e32 v82, v8, v82
	v_add_f32_e32 v120, v82, v83
	v_pk_mul_f32 v[82:83], v[0:1], v[128:129]
	s_nop 0
	v_add_f32_e32 v82, v9, v82
	v_add_f32_e32 v124, v82, v83
	v_pk_mul_f32 v[82:83], v[76:77], v[152:153]
	s_nop 0
	v_add_f32_e32 v82, v10, v82
	v_add_f32_e32 v128, v82, v83
	v_pk_mul_f32 v[82:83], v[2:3], v[86:87]
	s_nop 0
	v_add_f32_e32 v82, v11, v82
	v_add_f32_e32 v148, v82, v83
	v_pk_mul_f32 v[82:83], v[112:113], v[78:79]
	s_nop 0
	v_add_f32_e32 v82, v20, v82
	v_add_f32_e32 v86, v82, v83
	s_waitcnt vmcnt(15)
	v_lshlrev_b32_e32 v82, 16, v68
	s_waitcnt vmcnt(14)
	v_lshlrev_b32_e32 v83, 16, v72
	v_pk_mov_b32 v[78:79], v[78:79], v[82:83] op_sel:[1,0]
	s_nop 0
	v_pk_mul_f32 v[84:85], v[114:115], v[78:79]
	s_nop 0
	v_add_f32_e32 v84, v100, v84
	v_add_f32_e32 v104, v84, v85
	v_pk_mul_f32 v[84:85], v[114:115], v[82:83]
	s_nop 0
	v_add_f32_e32 v84, v86, v84
	v_add_f32_e32 v149, v84, v85
	v_pk_mul_f32 v[84:85], v[12:13], v[102:103]
	s_nop 0
	v_add_f32_e32 v84, v21, v84
	v_add_f32_e32 v105, v84, v85
	v_and_b32_e32 v85, 0xffff0000, v72
	v_and_b32_e32 v84, 0xffff0000, v68
	v_pk_mov_b32 v[86:87], v[102:103], v[84:85] op_sel:[1,0]
	s_nop 0
	v_pk_mul_f32 v[100:101], v[16:17], v[86:87]
	s_nop 0
	v_add_f32_e32 v68, v106, v100
	v_add_f32_e32 v68, v68, v101
	v_pk_mul_f32 v[100:101], v[16:17], v[84:85]
	v_cvt_pk_bf16_f32 v68, v104, v68
	s_nop 0
	v_add_f32_e32 v72, v105, v100
	v_add_f32_e32 v150, v72, v101
	v_pk_mul_f32 v[100:101], v[92:93], v[118:119]
	s_nop 0
	v_add_f32_e32 v72, v22, v100
	v_add_f32_e32 v72, v72, v101
	v_lshlrev_b32_e32 v100, 16, v69
	v_lshlrev_b32_e32 v101, 16, v73
	v_pk_mov_b32 v[102:103], v[118:119], v[100:101] op_sel:[1,0]
	v_and_b32_e32 v73, 0xffff0000, v73
	v_pk_mul_f32 v[104:105], v[96:97], v[102:103]
	s_nop 0
	v_add_f32_e32 v104, v107, v104
	v_add_f32_e32 v106, v104, v105
	v_pk_mul_f32 v[104:105], v[96:97], v[100:101]
	s_nop 0
	v_add_f32_e32 v72, v72, v104
	v_add_f32_e32 v151, v72, v105
	v_pk_mul_f32 v[104:105], v[14:15], v[88:89]
	s_nop 0
	v_add_f32_e32 v72, v23, v104
	v_add_f32_e32 v107, v72, v105
	v_and_b32_e32 v72, 0xffff0000, v69
	v_pk_mov_b32 v[88:89], v[88:89], v[72:73] op_sel:[1,0]
	s_nop 0
	v_pk_mul_f32 v[104:105], v[18:19], v[88:89]
	s_nop 0
	v_add_f32_e32 v69, v116, v104
	v_add_f32_e32 v69, v69, v105
	v_pk_mul_f32 v[104:105], v[18:19], v[72:73]
	v_cvt_pk_bf16_f32 v69, v106, v69
	s_nop 0
	v_add_f32_e32 v104, v107, v104
	v_add_f32_e32 v152, v104, v105
	v_pk_mul_f32 v[104:105], v[94:95], v[122:123]
	s_nop 0
	v_add_f32_e32 v104, v8, v104
	v_add_f32_e32 v118, v104, v105
	v_lshlrev_b32_e32 v104, 16, v70
	v_lshlrev_b32_e32 v105, 16, v74
	v_pk_mov_b32 v[106:107], v[122:123], v[104:105] op_sel:[1,0]
	s_nop 0
	v_pk_mul_f32 v[116:117], v[98:99], v[106:107]
	s_nop 0
	v_add_f32_e32 v116, v120, v116
	v_add_f32_e32 v122, v116, v117
	v_pk_mul_f32 v[116:117], v[98:99], v[104:105]
	s_nop 0
	v_add_f32_e32 v116, v118, v116
	v_add_f32_e32 v153, v116, v117
	v_pk_mul_f32 v[116:117], v[0:1], v[126:127]
	s_nop 0
	v_add_f32_e32 v116, v9, v116
	v_add_f32_e32 v123, v116, v117
	v_and_b32_e32 v117, 0xffff0000, v74
	v_and_b32_e32 v116, 0xffff0000, v70
	v_pk_mov_b32 v[118:119], v[126:127], v[116:117] op_sel:[1,0]
	s_nop 0
	v_pk_mul_f32 v[120:121], v[4:5], v[118:119]
	s_nop 0
	v_add_f32_e32 v70, v124, v120
	v_add_f32_e32 v70, v70, v121
	v_pk_mul_f32 v[120:121], v[4:5], v[116:117]
	v_cvt_pk_bf16_f32 v70, v122, v70
	s_nop 0
	v_add_f32_e32 v74, v123, v120
	v_add_f32_e32 v154, v74, v121
	v_pk_mul_f32 v[120:121], v[76:77], v[130:131]
	s_nop 0
	v_add_f32_e32 v74, v10, v120
	v_add_f32_e32 v74, v74, v121
	v_lshlrev_b32_e32 v120, 16, v71
	v_lshlrev_b32_e32 v121, 16, v75
	v_pk_mov_b32 v[122:123], v[130:131], v[120:121] op_sel:[1,0]
	v_and_b32_e32 v75, 0xffff0000, v75
	v_pk_mul_f32 v[124:125], v[80:81], v[122:123]
	s_nop 0
	v_add_f32_e32 v124, v128, v124
	v_add_f32_e32 v130, v124, v125
	v_pk_mul_f32 v[124:125], v[80:81], v[120:121]
	s_nop 0
	v_add_f32_e32 v124, v74, v124
	v_and_b32_e32 v74, 0xffff0000, v71
	v_pk_mov_b32 v[126:127], v[90:91], v[74:75] op_sel:[1,0]
	v_pk_mul_f32 v[90:91], v[2:3], v[90:91]
	v_pk_mul_f32 v[128:129], v[6:7], v[126:127]
	v_add_f32_e32 v90, v11, v90
	v_add_f32_e32 v71, v148, v128
	v_add_f32_e32 v71, v71, v129
	v_mov_b32_e32 v128, s0
	v_mov_b32_e32 v129, s1
	v_cvt_pk_bf16_f32 v71, v130, v71
	v_add_f32_e32 v124, v124, v125
	v_readfirstlane_b32 s16, v128
	v_readfirstlane_b32 s17, v129
	s_load_dwordx2 s[16:17], s[16:17], 0xc0
	v_add_f32_e32 v125, v90, v91
	s_waitcnt lgkmcnt(0)
	v_mov_b64_e32 v[90:91], s[16:17]
	v_mad_i64_i32 v[90:91], s[16:17], v147, s24, v[90:91]
	v_lshl_add_u64 v[90:91], v[90:91], 0, v[110:111]
	v_add_co_u32_e32 v90, vcc, s26, v90
	s_nop 1
	v_addc_co_u32_e32 v91, vcc, 0, v91, vcc
	global_store_dwordx4 v[90:91], v[68:71], off sc1
	v_mov_b32_e32 v90, s0
	v_mov_b32_e32 v91, s1
	v_pk_mul_f32 v[68:69], v[6:7], v[74:75]
	s_nop 0
	v_add_f32_e32 v68, v125, v68
	v_add_f32_e32 v71, v68, v69
	v_cvt_pk_bf16_f32 v68, v149, v150
	v_cvt_pk_bf16_f32 v69, v151, v152
	v_cvt_pk_bf16_f32 v70, v153, v154
	v_cvt_pk_bf16_f32 v71, v124, v71
	s_nop 0
	v_readfirstlane_b32 s16, v90
	v_readfirstlane_b32 s17, v91
	s_load_dwordx2 s[16:17], s[16:17], 0xc0
	s_waitcnt lgkmcnt(0)
	v_mov_b64_e32 v[90:91], s[16:17]
	v_mad_i64_i32 v[90:91], s[16:17], v146, s24, v[90:91]
	v_lshl_add_u64 v[90:91], v[90:91], 0, v[110:111]
	v_add_co_u32_e32 v90, vcc, s26, v90
	s_nop 1
	v_addc_co_u32_e32 v91, vcc, 0, v91, vcc
	global_store_dwordx4 v[90:91], v[68:71], off sc1
	s_nop 1
	v_pk_mul_f32 v[68:69], v[112:113], v[78:79]
	s_nop 0
	v_add_f32_e32 v68, v20, v68
	v_add_f32_e32 v90, v68, v69
	v_pk_mul_f32 v[68:69], v[12:13], v[86:87]
	s_nop 0
	v_add_f32_e32 v68, v21, v68
	v_add_f32_e32 v86, v68, v69
	v_pk_mul_f32 v[68:69], v[92:93], v[102:103]
	s_nop 0
	v_add_f32_e32 v68, v22, v68
	v_add_f32_e32 v91, v68, v69
	v_pk_mul_f32 v[68:69], v[14:15], v[88:89]
	s_nop 0
	v_add_f32_e32 v68, v23, v68
	v_add_f32_e32 v102, v68, v69
	v_pk_mul_f32 v[68:69], v[94:95], v[106:107]
	s_nop 0
	v_add_f32_e32 v68, v8, v68
	v_add_f32_e32 v103, v68, v69
	v_pk_mul_f32 v[68:69], v[0:1], v[118:119]
	s_nop 0
	v_add_f32_e32 v68, v9, v68
	v_add_f32_e32 v106, v68, v69
	v_pk_mul_f32 v[68:69], v[76:77], v[122:123]
	s_nop 0
	v_add_f32_e32 v68, v10, v68
	v_add_f32_e32 v118, v68, v69
	v_pk_mul_f32 v[68:69], v[2:3], v[126:127]
	s_nop 0
	v_add_f32_e32 v68, v11, v68
	v_add_f32_e32 v122, v68, v69
	v_pk_mul_f32 v[68:69], v[112:113], v[82:83]
	s_nop 0
	v_add_f32_e32 v68, v20, v68
	v_add_f32_e32 v87, v68, v69
	s_waitcnt vmcnt(15)
	v_lshlrev_b32_e32 v68, 16, v60
	s_waitcnt vmcnt(14)
	v_lshlrev_b32_e32 v69, 16, v64
	v_pk_mov_b32 v[70:71], v[82:83], v[68:69] op_sel:[1,0]
	s_nop 0
	v_pk_mul_f32 v[78:79], v[114:115], v[70:71]
	s_nop 0
	v_add_f32_e32 v78, v90, v78
	v_add_f32_e32 v88, v78, v79
	v_pk_mul_f32 v[78:79], v[114:115], v[68:69]
	s_nop 0
	v_add_f32_e32 v78, v87, v78
	v_add_f32_e32 v123, v78, v79
	v_pk_mul_f32 v[78:79], v[12:13], v[84:85]
	s_nop 0
	v_add_f32_e32 v78, v21, v78
	v_add_f32_e32 v87, v78, v79
	v_and_b32_e32 v79, 0xffff0000, v64
	v_and_b32_e32 v78, 0xffff0000, v60
	v_pk_mov_b32 v[82:83], v[84:85], v[78:79] op_sel:[1,0]
	s_nop 0
	v_pk_mul_f32 v[84:85], v[16:17], v[82:83]
	s_nop 0
	v_add_f32_e32 v60, v86, v84
	v_add_f32_e32 v60, v60, v85
	v_pk_mul_f32 v[84:85], v[16:17], v[78:79]
	v_cvt_pk_bf16_f32 v60, v88, v60
	s_nop 0
	v_add_f32_e32 v64, v87, v84
	v_add_f32_e32 v124, v64, v85
	v_pk_mul_f32 v[84:85], v[92:93], v[100:101]
	s_nop 0
	v_add_f32_e32 v64, v22, v84
	v_add_f32_e32 v64, v64, v85
	v_lshlrev_b32_e32 v84, 16, v61
	v_lshlrev_b32_e32 v85, 16, v65
	v_pk_mov_b32 v[86:87], v[100:101], v[84:85] op_sel:[1,0]
	v_and_b32_e32 v65, 0xffff0000, v65
	v_pk_mul_f32 v[88:89], v[96:97], v[86:87]
	s_nop 0
	v_add_f32_e32 v88, v91, v88
	v_add_f32_e32 v90, v88, v89
	v_pk_mul_f32 v[88:89], v[96:97], v[84:85]
	s_nop 0
	v_add_f32_e32 v64, v64, v88
	v_add_f32_e32 v125, v64, v89
	v_pk_mul_f32 v[88:89], v[14:15], v[72:73]
	s_nop 0
	v_add_f32_e32 v64, v23, v88
	v_add_f32_e32 v91, v64, v89
	v_and_b32_e32 v64, 0xffff0000, v61
	v_pk_mov_b32 v[72:73], v[72:73], v[64:65] op_sel:[1,0]
	s_nop 0
	v_pk_mul_f32 v[88:89], v[18:19], v[72:73]
	s_nop 0
	v_add_f32_e32 v61, v102, v88
	v_add_f32_e32 v61, v61, v89
	v_pk_mul_f32 v[88:89], v[18:19], v[64:65]
	v_cvt_pk_bf16_f32 v61, v90, v61
	s_nop 0
	v_add_f32_e32 v88, v91, v88
	v_add_f32_e32 v126, v88, v89
	v_pk_mul_f32 v[88:89], v[94:95], v[104:105]
	s_nop 0
	v_add_f32_e32 v88, v8, v88
	v_add_f32_e32 v102, v88, v89
	v_lshlrev_b32_e32 v88, 16, v62
	v_lshlrev_b32_e32 v89, 16, v66
	v_pk_mov_b32 v[90:91], v[104:105], v[88:89] op_sel:[1,0]
	s_nop 0
	v_pk_mul_f32 v[100:101], v[98:99], v[90:91]
	s_nop 0
	v_add_f32_e32 v100, v103, v100
	v_add_f32_e32 v107, v100, v101
	v_pk_mul_f32 v[100:101], v[98:99], v[88:89]
	s_nop 0
	v_add_f32_e32 v100, v102, v100
	v_add_f32_e32 v127, v100, v101
	v_pk_mul_f32 v[100:101], v[0:1], v[116:117]
	s_nop 0
	v_add_f32_e32 v100, v9, v100
	v_add_f32_e32 v119, v100, v101
	v_and_b32_e32 v101, 0xffff0000, v66
	v_and_b32_e32 v100, 0xffff0000, v62
	v_pk_mov_b32 v[102:103], v[116:117], v[100:101] op_sel:[1,0]
	s_nop 0
	v_pk_mul_f32 v[104:105], v[4:5], v[102:103]
	s_nop 0
	v_add_f32_e32 v62, v106, v104
	v_add_f32_e32 v62, v62, v105
	v_pk_mul_f32 v[104:105], v[4:5], v[100:101]
	v_cvt_pk_bf16_f32 v62, v107, v62
	s_nop 0
	v_add_f32_e32 v66, v119, v104
	v_add_f32_e32 v128, v66, v105
	v_pk_mul_f32 v[104:105], v[76:77], v[120:121]
	s_nop 0
	v_add_f32_e32 v66, v10, v104
	v_add_f32_e32 v66, v66, v105
	v_lshlrev_b32_e32 v104, 16, v63
	v_lshlrev_b32_e32 v105, 16, v67
	v_pk_mov_b32 v[106:107], v[120:121], v[104:105] op_sel:[1,0]
	v_and_b32_e32 v67, 0xffff0000, v67
	v_pk_mul_f32 v[116:117], v[80:81], v[106:107]
	s_nop 0
	v_add_f32_e32 v116, v118, v116
	v_add_f32_e32 v129, v116, v117
	v_pk_mul_f32 v[116:117], v[80:81], v[104:105]
	s_nop 0
	v_add_f32_e32 v116, v66, v116
	v_and_b32_e32 v66, 0xffff0000, v63
	v_pk_mov_b32 v[118:119], v[74:75], v[66:67] op_sel:[1,0]
	v_pk_mul_f32 v[74:75], v[2:3], v[74:75]
	v_pk_mul_f32 v[120:121], v[6:7], v[118:119]
	v_add_f32_e32 v74, v11, v74
	v_add_f32_e32 v63, v122, v120
	v_add_f32_e32 v63, v63, v121
	v_mov_b32_e32 v120, s0
	v_mov_b32_e32 v121, s1
	v_cvt_pk_bf16_f32 v63, v129, v63
	v_add_f32_e32 v116, v116, v117
	v_readfirstlane_b32 s16, v120
	v_readfirstlane_b32 s17, v121
	s_load_dwordx2 s[16:17], s[16:17], 0xc0
	v_add_f32_e32 v117, v74, v75
	s_waitcnt lgkmcnt(0)
	v_mov_b64_e32 v[74:75], s[16:17]
	v_mad_i64_i32 v[74:75], s[16:17], v145, s24, v[74:75]
	v_lshl_add_u64 v[74:75], v[74:75], 0, v[110:111]
	v_add_co_u32_e32 v74, vcc, s26, v74
	s_nop 1
	v_addc_co_u32_e32 v75, vcc, 0, v75, vcc
	global_store_dwordx4 v[74:75], v[60:63], off sc1
	v_mov_b32_e32 v74, s0
	v_mov_b32_e32 v75, s1
	v_pk_mul_f32 v[60:61], v[6:7], v[66:67]
	s_nop 0
	v_add_f32_e32 v60, v117, v60
	v_add_f32_e32 v63, v60, v61
	v_cvt_pk_bf16_f32 v60, v123, v124
	v_cvt_pk_bf16_f32 v61, v125, v126
	v_cvt_pk_bf16_f32 v62, v127, v128
	v_cvt_pk_bf16_f32 v63, v116, v63
	s_nop 0
	v_readfirstlane_b32 s16, v74
	v_readfirstlane_b32 s17, v75
	s_load_dwordx2 s[16:17], s[16:17], 0xc0
	s_waitcnt lgkmcnt(0)
	v_mov_b64_e32 v[74:75], s[16:17]
	v_mad_i64_i32 v[74:75], s[16:17], v144, s24, v[74:75]
	v_lshl_add_u64 v[74:75], v[74:75], 0, v[110:111]
	v_add_co_u32_e32 v74, vcc, s26, v74
	s_nop 1
	v_addc_co_u32_e32 v75, vcc, 0, v75, vcc
	global_store_dwordx4 v[74:75], v[60:63], off sc1
	s_nop 1
	v_pk_mul_f32 v[60:61], v[112:113], v[70:71]
	s_nop 0
	v_add_f32_e32 v60, v20, v60
	v_add_f32_e32 v70, v60, v61
	v_pk_mul_f32 v[60:61], v[12:13], v[82:83]
	s_nop 0
	v_add_f32_e32 v60, v21, v60
	v_add_f32_e32 v74, v60, v61
	v_pk_mul_f32 v[60:61], v[92:93], v[86:87]
	s_nop 0
	v_add_f32_e32 v60, v22, v60
	v_add_f32_e32 v82, v60, v61
	v_pk_mul_f32 v[60:61], v[14:15], v[72:73]
	s_nop 0
	v_add_f32_e32 v60, v23, v60
	v_add_f32_e32 v83, v60, v61
	v_pk_mul_f32 v[60:61], v[94:95], v[90:91]
	s_nop 0
	v_add_f32_e32 v60, v8, v60
	v_add_f32_e32 v86, v60, v61
	v_pk_mul_f32 v[60:61], v[0:1], v[102:103]
	s_nop 0
	v_add_f32_e32 v60, v9, v60
	v_add_f32_e32 v90, v60, v61
	v_pk_mul_f32 v[60:61], v[76:77], v[106:107]
	s_nop 0
	v_add_f32_e32 v60, v10, v60
	v_add_f32_e32 v102, v60, v61
	v_pk_mul_f32 v[60:61], v[2:3], v[118:119]
	s_nop 0
	v_add_f32_e32 v60, v11, v60
	v_add_f32_e32 v106, v60, v61
	v_pk_mul_f32 v[60:61], v[112:113], v[68:69]
	s_nop 0
	v_add_f32_e32 v60, v20, v60
	v_add_f32_e32 v71, v60, v61
	s_waitcnt vmcnt(15)
	v_lshlrev_b32_e32 v60, 16, v52
	s_waitcnt vmcnt(14)
	v_lshlrev_b32_e32 v61, 16, v56
	v_pk_mov_b32 v[62:63], v[68:69], v[60:61] op_sel:[1,0]
	s_nop 0
	v_pk_mul_f32 v[68:69], v[114:115], v[62:63]
	s_nop 0
	v_add_f32_e32 v68, v70, v68
	v_add_f32_e32 v75, v68, v69
	v_pk_mul_f32 v[68:69], v[114:115], v[60:61]
	s_nop 0
	v_add_f32_e32 v68, v71, v68
	v_add_f32_e32 v107, v68, v69
	v_pk_mul_f32 v[68:69], v[12:13], v[78:79]
	s_nop 0
	v_add_f32_e32 v68, v21, v68
	v_add_f32_e32 v87, v68, v69
	v_and_b32_e32 v69, 0xffff0000, v56
	v_and_b32_e32 v68, 0xffff0000, v52
	v_pk_mov_b32 v[70:71], v[78:79], v[68:69] op_sel:[1,0]
	s_nop 0
	v_pk_mul_f32 v[72:73], v[16:17], v[70:71]
	s_nop 0
	v_add_f32_e32 v52, v74, v72
	v_add_f32_e32 v52, v52, v73
	v_pk_mul_f32 v[72:73], v[16:17], v[68:69]
	v_cvt_pk_bf16_f32 v52, v75, v52
	s_nop 0
	v_add_f32_e32 v56, v87, v72
	v_add_f32_e32 v116, v56, v73
	v_pk_mul_f32 v[72:73], v[92:93], v[84:85]
	s_nop 0
	v_add_f32_e32 v56, v22, v72
	v_add_f32_e32 v56, v56, v73
	v_lshlrev_b32_e32 v72, 16, v53
	v_lshlrev_b32_e32 v73, 16, v57
	v_pk_mov_b32 v[74:75], v[84:85], v[72:73] op_sel:[1,0]
	v_and_b32_e32 v57, 0xffff0000, v57
	v_pk_mul_f32 v[78:79], v[96:97], v[74:75]
	s_nop 0
	v_add_f32_e32 v78, v82, v78
	v_add_f32_e32 v82, v78, v79
	v_pk_mul_f32 v[78:79], v[96:97], v[72:73]
	s_nop 0
	v_add_f32_e32 v56, v56, v78
	v_add_f32_e32 v117, v56, v79
	v_pk_mul_f32 v[78:79], v[14:15], v[64:65]
	s_nop 0
	v_add_f32_e32 v56, v23, v78
	v_add_f32_e32 v84, v56, v79
	v_and_b32_e32 v56, 0xffff0000, v53
	v_pk_mov_b32 v[64:65], v[64:65], v[56:57] op_sel:[1,0]
	s_nop 0
	v_pk_mul_f32 v[78:79], v[18:19], v[64:65]
	s_nop 0
	v_add_f32_e32 v53, v83, v78
	v_add_f32_e32 v53, v53, v79
	v_pk_mul_f32 v[78:79], v[18:19], v[56:57]
	v_cvt_pk_bf16_f32 v53, v82, v53
	s_nop 0
	v_add_f32_e32 v78, v84, v78
	v_add_f32_e32 v118, v78, v79
	v_pk_mul_f32 v[78:79], v[94:95], v[88:89]
	s_nop 0
	v_add_f32_e32 v78, v8, v78
	v_add_f32_e32 v87, v78, v79
	v_lshlrev_b32_e32 v78, 16, v54
	v_lshlrev_b32_e32 v79, 16, v58
	v_pk_mov_b32 v[82:83], v[88:89], v[78:79] op_sel:[1,0]
	s_nop 0
	v_pk_mul_f32 v[84:85], v[98:99], v[82:83]
	s_nop 0
	v_add_f32_e32 v84, v86, v84
	v_add_f32_e32 v91, v84, v85
	v_pk_mul_f32 v[84:85], v[98:99], v[78:79]
	s_nop 0
	v_add_f32_e32 v84, v87, v84
	v_add_f32_e32 v119, v84, v85
	v_pk_mul_f32 v[84:85], v[0:1], v[100:101]
	s_nop 0
	v_add_f32_e32 v84, v9, v84
	v_add_f32_e32 v103, v84, v85
	v_and_b32_e32 v85, 0xffff0000, v58
	v_and_b32_e32 v84, 0xffff0000, v54
	v_pk_mov_b32 v[86:87], v[100:101], v[84:85] op_sel:[1,0]
	s_nop 0
	v_pk_mul_f32 v[88:89], v[4:5], v[86:87]
	s_nop 0
	v_add_f32_e32 v54, v90, v88
	v_add_f32_e32 v54, v54, v89
	v_pk_mul_f32 v[88:89], v[4:5], v[84:85]
	v_cvt_pk_bf16_f32 v54, v91, v54
	s_nop 0
	v_add_f32_e32 v58, v103, v88
	v_add_f32_e32 v120, v58, v89
	v_pk_mul_f32 v[88:89], v[76:77], v[104:105]
	s_nop 0
	v_add_f32_e32 v58, v10, v88
	v_add_f32_e32 v58, v58, v89
	v_lshlrev_b32_e32 v88, 16, v55
	v_lshlrev_b32_e32 v89, 16, v59
	v_pk_mov_b32 v[90:91], v[104:105], v[88:89] op_sel:[1,0]
	v_and_b32_e32 v59, 0xffff0000, v59
	v_pk_mul_f32 v[100:101], v[80:81], v[90:91]
	s_nop 0
	v_add_f32_e32 v100, v102, v100
	v_add_f32_e32 v121, v100, v101
	v_pk_mul_f32 v[100:101], v[80:81], v[88:89]
	s_nop 0
	v_add_f32_e32 v100, v58, v100
	v_and_b32_e32 v58, 0xffff0000, v55
	v_pk_mov_b32 v[102:103], v[66:67], v[58:59] op_sel:[1,0]
	v_pk_mul_f32 v[66:67], v[2:3], v[66:67]
	v_pk_mul_f32 v[104:105], v[6:7], v[102:103]
	v_add_f32_e32 v66, v11, v66
	v_add_f32_e32 v55, v106, v104
	v_add_f32_e32 v55, v55, v105
	v_mov_b32_e32 v104, s0
	v_mov_b32_e32 v105, s1
	v_cvt_pk_bf16_f32 v55, v121, v55
	v_add_f32_e32 v100, v100, v101
	v_readfirstlane_b32 s16, v104
	v_readfirstlane_b32 s17, v105
	s_load_dwordx2 s[16:17], s[16:17], 0xc0
	v_add_f32_e32 v101, v66, v67
	s_waitcnt lgkmcnt(0)
	v_mov_b64_e32 v[66:67], s[16:17]
	v_mad_i64_i32 v[66:67], s[16:17], v143, s24, v[66:67]
	v_lshl_add_u64 v[66:67], v[66:67], 0, v[110:111]
	v_add_co_u32_e32 v66, vcc, s26, v66
	s_nop 1
	v_addc_co_u32_e32 v67, vcc, 0, v67, vcc
	global_store_dwordx4 v[66:67], v[52:55], off sc1
	v_mov_b32_e32 v66, s0
	v_mov_b32_e32 v67, s1
	v_pk_mul_f32 v[52:53], v[6:7], v[58:59]
	s_nop 0
	v_add_f32_e32 v52, v101, v52
	v_add_f32_e32 v55, v52, v53
	v_cvt_pk_bf16_f32 v52, v107, v116
	v_cvt_pk_bf16_f32 v53, v117, v118
	v_cvt_pk_bf16_f32 v54, v119, v120
	v_cvt_pk_bf16_f32 v55, v100, v55
	s_nop 0
	v_readfirstlane_b32 s16, v66
	v_readfirstlane_b32 s17, v67
	s_load_dwordx2 s[16:17], s[16:17], 0xc0
	s_waitcnt lgkmcnt(0)
	v_mov_b64_e32 v[66:67], s[16:17]
	v_mad_i64_i32 v[66:67], s[16:17], v142, s24, v[66:67]
	v_lshl_add_u64 v[66:67], v[66:67], 0, v[110:111]
	v_add_co_u32_e32 v66, vcc, s26, v66
	s_nop 1
	v_addc_co_u32_e32 v67, vcc, 0, v67, vcc
	global_store_dwordx4 v[66:67], v[52:55], off sc1
	s_nop 1
	v_pk_mul_f32 v[52:53], v[112:113], v[62:63]
	s_nop 0
	v_add_f32_e32 v52, v20, v52
	v_add_f32_e32 v62, v52, v53
	v_pk_mul_f32 v[52:53], v[12:13], v[70:71]
	s_nop 0
	v_add_f32_e32 v52, v21, v52
	v_add_f32_e32 v66, v52, v53
	v_pk_mul_f32 v[52:53], v[92:93], v[74:75]
	s_nop 0
	v_add_f32_e32 v52, v22, v52
	v_add_f32_e32 v70, v52, v53
	v_pk_mul_f32 v[52:53], v[14:15], v[64:65]
	s_nop 0
	v_add_f32_e32 v52, v23, v52
	v_add_f32_e32 v71, v52, v53
	v_pk_mul_f32 v[52:53], v[94:95], v[82:83]
	s_nop 0
	v_add_f32_e32 v52, v8, v52
	v_add_f32_e32 v74, v52, v53
	v_pk_mul_f32 v[52:53], v[0:1], v[86:87]
	s_nop 0
	v_add_f32_e32 v52, v9, v52
	v_add_f32_e32 v82, v52, v53
	v_pk_mul_f32 v[52:53], v[76:77], v[90:91]
	s_nop 0
	v_add_f32_e32 v52, v10, v52
	v_add_f32_e32 v86, v52, v53
	v_pk_mul_f32 v[52:53], v[2:3], v[102:103]
	s_nop 0
	v_add_f32_e32 v52, v11, v52
	v_add_f32_e32 v90, v52, v53
	v_pk_mul_f32 v[52:53], v[112:113], v[60:61]
	s_nop 0
	v_add_f32_e32 v52, v20, v52
	v_add_f32_e32 v63, v52, v53
	s_waitcnt vmcnt(15)
	v_lshlrev_b32_e32 v52, 16, v44
	s_waitcnt vmcnt(14)
	v_lshlrev_b32_e32 v53, 16, v48
	v_pk_mov_b32 v[54:55], v[60:61], v[52:53] op_sel:[1,0]
	s_nop 0
	v_pk_mul_f32 v[60:61], v[114:115], v[54:55]
	s_nop 0
	v_add_f32_e32 v60, v62, v60
	v_add_f32_e32 v67, v60, v61
	v_pk_mul_f32 v[60:61], v[114:115], v[52:53]
	s_nop 0
	v_add_f32_e32 v60, v63, v60
	v_add_f32_e32 v91, v60, v61
	v_pk_mul_f32 v[60:61], v[12:13], v[68:69]
	s_nop 0
	v_add_f32_e32 v60, v21, v60
	v_add_f32_e32 v75, v60, v61
	v_and_b32_e32 v61, 0xffff0000, v48
	v_and_b32_e32 v60, 0xffff0000, v44
	v_pk_mov_b32 v[62:63], v[68:69], v[60:61] op_sel:[1,0]
	s_nop 0
	v_pk_mul_f32 v[64:65], v[16:17], v[62:63]
	s_nop 0
	v_add_f32_e32 v44, v66, v64
	v_add_f32_e32 v44, v44, v65
	v_pk_mul_f32 v[64:65], v[16:17], v[60:61]
	v_cvt_pk_bf16_f32 v44, v67, v44
	s_nop 0
	v_add_f32_e32 v48, v75, v64
	v_add_f32_e32 v100, v48, v65
	v_pk_mul_f32 v[64:65], v[92:93], v[72:73]
	s_nop 0
	v_add_f32_e32 v48, v22, v64
	v_add_f32_e32 v48, v48, v65
	v_lshlrev_b32_e32 v64, 16, v45
	v_lshlrev_b32_e32 v65, 16, v49
	v_pk_mov_b32 v[66:67], v[72:73], v[64:65] op_sel:[1,0]
	v_and_b32_e32 v49, 0xffff0000, v49
	v_pk_mul_f32 v[68:69], v[96:97], v[66:67]
	s_nop 0
	v_add_f32_e32 v68, v70, v68
	v_add_f32_e32 v70, v68, v69
	v_pk_mul_f32 v[68:69], v[96:97], v[64:65]
	s_nop 0
	v_add_f32_e32 v48, v48, v68
	v_add_f32_e32 v101, v48, v69
	v_pk_mul_f32 v[68:69], v[14:15], v[56:57]
	s_nop 0
	v_add_f32_e32 v48, v23, v68
	v_add_f32_e32 v72, v48, v69
	v_and_b32_e32 v48, 0xffff0000, v45
	v_pk_mov_b32 v[56:57], v[56:57], v[48:49] op_sel:[1,0]
	s_nop 0
	v_pk_mul_f32 v[68:69], v[18:19], v[56:57]
	s_nop 0
	v_add_f32_e32 v45, v71, v68
	v_add_f32_e32 v45, v45, v69
	v_pk_mul_f32 v[68:69], v[18:19], v[48:49]
	v_cvt_pk_bf16_f32 v45, v70, v45
	s_nop 0
	v_add_f32_e32 v68, v72, v68
	v_add_f32_e32 v102, v68, v69
	v_pk_mul_f32 v[68:69], v[94:95], v[78:79]
	s_nop 0
	v_add_f32_e32 v68, v8, v68
	v_add_f32_e32 v75, v68, v69
	v_lshlrev_b32_e32 v68, 16, v46
	v_lshlrev_b32_e32 v69, 16, v50
	v_pk_mov_b32 v[70:71], v[78:79], v[68:69] op_sel:[1,0]
	s_nop 0
	v_pk_mul_f32 v[72:73], v[98:99], v[70:71]
	s_nop 0
	v_add_f32_e32 v72, v74, v72
	v_add_f32_e32 v83, v72, v73
	v_pk_mul_f32 v[72:73], v[98:99], v[68:69]
	s_nop 0
	v_add_f32_e32 v72, v75, v72
	v_add_f32_e32 v103, v72, v73
	v_pk_mul_f32 v[72:73], v[0:1], v[84:85]
	s_nop 0
	v_add_f32_e32 v72, v9, v72
	v_add_f32_e32 v87, v72, v73
	v_and_b32_e32 v73, 0xffff0000, v50
	v_and_b32_e32 v72, 0xffff0000, v46
	v_pk_mov_b32 v[74:75], v[84:85], v[72:73] op_sel:[1,0]
	s_nop 0
	v_pk_mul_f32 v[78:79], v[4:5], v[74:75]
	s_nop 0
	v_add_f32_e32 v46, v82, v78
	v_add_f32_e32 v46, v46, v79
	v_pk_mul_f32 v[78:79], v[4:5], v[72:73]
	v_cvt_pk_bf16_f32 v46, v83, v46
	s_nop 0
	v_add_f32_e32 v50, v87, v78
	v_add_f32_e32 v104, v50, v79
	v_pk_mul_f32 v[78:79], v[76:77], v[88:89]
	s_nop 0
	v_add_f32_e32 v50, v10, v78
	v_add_f32_e32 v50, v50, v79
	v_lshlrev_b32_e32 v78, 16, v47
	v_lshlrev_b32_e32 v79, 16, v51
	v_pk_mov_b32 v[82:83], v[88:89], v[78:79] op_sel:[1,0]
	v_and_b32_e32 v51, 0xffff0000, v51
	v_pk_mul_f32 v[84:85], v[80:81], v[82:83]
	s_nop 0
	v_add_f32_e32 v84, v86, v84
	v_add_f32_e32 v105, v84, v85
	v_pk_mul_f32 v[84:85], v[80:81], v[78:79]
	s_nop 0
	v_add_f32_e32 v84, v50, v84
	v_and_b32_e32 v50, 0xffff0000, v47
	v_pk_mov_b32 v[86:87], v[58:59], v[50:51] op_sel:[1,0]
	v_pk_mul_f32 v[58:59], v[2:3], v[58:59]
	v_pk_mul_f32 v[88:89], v[6:7], v[86:87]
	v_add_f32_e32 v58, v11, v58
	v_add_f32_e32 v47, v90, v88
	v_add_f32_e32 v47, v47, v89
	v_mov_b32_e32 v88, s0
	v_mov_b32_e32 v89, s1
	v_cvt_pk_bf16_f32 v47, v105, v47
	v_add_f32_e32 v84, v84, v85
	v_readfirstlane_b32 s16, v88
	v_readfirstlane_b32 s17, v89
	s_load_dwordx2 s[16:17], s[16:17], 0xc0
	v_add_f32_e32 v85, v58, v59
	s_waitcnt lgkmcnt(0)
	v_mov_b64_e32 v[58:59], s[16:17]
	v_mad_i64_i32 v[58:59], s[16:17], v141, s24, v[58:59]
	v_lshl_add_u64 v[58:59], v[58:59], 0, v[110:111]
	v_add_co_u32_e32 v58, vcc, s26, v58
	s_nop 1
	v_addc_co_u32_e32 v59, vcc, 0, v59, vcc
	global_store_dwordx4 v[58:59], v[44:47], off sc1
	v_mov_b32_e32 v58, s0
	v_mov_b32_e32 v59, s1
	v_pk_mul_f32 v[44:45], v[6:7], v[50:51]
	s_nop 0
	v_add_f32_e32 v44, v85, v44
	v_add_f32_e32 v47, v44, v45
	v_cvt_pk_bf16_f32 v44, v91, v100
	v_cvt_pk_bf16_f32 v45, v101, v102
	v_cvt_pk_bf16_f32 v46, v103, v104
	v_cvt_pk_bf16_f32 v47, v84, v47
	s_nop 0
	v_readfirstlane_b32 s16, v58
	v_readfirstlane_b32 s17, v59
	s_load_dwordx2 s[16:17], s[16:17], 0xc0
	s_waitcnt lgkmcnt(0)
	v_mov_b64_e32 v[58:59], s[16:17]
	v_mad_i64_i32 v[58:59], s[16:17], v140, s24, v[58:59]
	v_lshl_add_u64 v[58:59], v[58:59], 0, v[110:111]
	v_add_co_u32_e32 v58, vcc, s26, v58
	s_nop 1
	v_addc_co_u32_e32 v59, vcc, 0, v59, vcc
	global_store_dwordx4 v[58:59], v[44:47], off sc1
	s_nop 1
	v_pk_mul_f32 v[44:45], v[112:113], v[54:55]
	s_nop 0
	v_add_f32_e32 v44, v20, v44
	v_add_f32_e32 v54, v44, v45
	v_pk_mul_f32 v[44:45], v[12:13], v[62:63]
	s_nop 0
	v_add_f32_e32 v44, v21, v44
	v_add_f32_e32 v58, v44, v45
	v_pk_mul_f32 v[44:45], v[92:93], v[66:67]
	s_nop 0
	v_add_f32_e32 v44, v22, v44
	v_add_f32_e32 v62, v44, v45
	v_pk_mul_f32 v[44:45], v[14:15], v[56:57]
	s_nop 0
	v_add_f32_e32 v44, v23, v44
	v_add_f32_e32 v63, v44, v45
	v_pk_mul_f32 v[44:45], v[94:95], v[70:71]
	s_nop 0
	v_add_f32_e32 v44, v8, v44
	v_add_f32_e32 v66, v44, v45
	v_pk_mul_f32 v[44:45], v[0:1], v[74:75]
	s_nop 0
	v_add_f32_e32 v44, v9, v44
	v_add_f32_e32 v70, v44, v45
	v_pk_mul_f32 v[44:45], v[76:77], v[82:83]
	s_nop 0
	v_add_f32_e32 v44, v10, v44
	v_add_f32_e32 v74, v44, v45
	v_pk_mul_f32 v[44:45], v[2:3], v[86:87]
	s_nop 0
	v_add_f32_e32 v44, v11, v44
	v_add_f32_e32 v82, v44, v45
	v_pk_mul_f32 v[44:45], v[112:113], v[52:53]
	s_nop 0
	v_add_f32_e32 v44, v20, v44
	v_add_f32_e32 v55, v44, v45
	s_waitcnt vmcnt(15)
	v_lshlrev_b32_e32 v44, 16, v36
	s_waitcnt vmcnt(14)
	v_lshlrev_b32_e32 v45, 16, v40
	v_pk_mov_b32 v[46:47], v[52:53], v[44:45] op_sel:[1,0]
	s_nop 0
	v_pk_mul_f32 v[52:53], v[114:115], v[46:47]
	s_nop 0
	v_add_f32_e32 v52, v54, v52
	v_add_f32_e32 v59, v52, v53
	v_pk_mul_f32 v[52:53], v[114:115], v[44:45]
	s_nop 0
	v_add_f32_e32 v52, v55, v52
	v_add_f32_e32 v83, v52, v53
	v_pk_mul_f32 v[52:53], v[12:13], v[60:61]
	s_nop 0
	v_add_f32_e32 v52, v21, v52
	v_add_f32_e32 v67, v52, v53
	v_and_b32_e32 v53, 0xffff0000, v40
	v_and_b32_e32 v52, 0xffff0000, v36
	v_pk_mov_b32 v[54:55], v[60:61], v[52:53] op_sel:[1,0]
	s_nop 0
	v_pk_mul_f32 v[56:57], v[16:17], v[54:55]
	s_nop 0
	v_add_f32_e32 v36, v58, v56
	v_add_f32_e32 v36, v36, v57
	v_pk_mul_f32 v[56:57], v[16:17], v[52:53]
	v_cvt_pk_bf16_f32 v36, v59, v36
	s_nop 0
	v_add_f32_e32 v40, v67, v56
	v_add_f32_e32 v84, v40, v57
	v_pk_mul_f32 v[56:57], v[92:93], v[64:65]
	s_nop 0
	v_add_f32_e32 v40, v22, v56
	v_add_f32_e32 v40, v40, v57
	v_lshlrev_b32_e32 v56, 16, v37
	v_lshlrev_b32_e32 v57, 16, v41
	v_pk_mov_b32 v[58:59], v[64:65], v[56:57] op_sel:[1,0]
	v_and_b32_e32 v41, 0xffff0000, v41
	v_pk_mul_f32 v[60:61], v[96:97], v[58:59]
	s_nop 0
	v_add_f32_e32 v60, v62, v60
	v_add_f32_e32 v62, v60, v61
	v_pk_mul_f32 v[60:61], v[96:97], v[56:57]
	s_nop 0
	v_add_f32_e32 v40, v40, v60
	v_add_f32_e32 v85, v40, v61
	v_pk_mul_f32 v[60:61], v[14:15], v[48:49]
	s_nop 0
	v_add_f32_e32 v40, v23, v60
	v_add_f32_e32 v64, v40, v61
	v_and_b32_e32 v40, 0xffff0000, v37
	v_pk_mov_b32 v[48:49], v[48:49], v[40:41] op_sel:[1,0]
	s_nop 0
	v_pk_mul_f32 v[60:61], v[18:19], v[48:49]
	s_nop 0
	v_add_f32_e32 v37, v63, v60
	v_add_f32_e32 v37, v37, v61
	v_pk_mul_f32 v[60:61], v[18:19], v[40:41]
	v_cvt_pk_bf16_f32 v37, v62, v37
	s_nop 0
	v_add_f32_e32 v60, v64, v60
	v_add_f32_e32 v86, v60, v61
	v_pk_mul_f32 v[60:61], v[94:95], v[68:69]
	s_nop 0
	v_add_f32_e32 v60, v8, v60
	v_add_f32_e32 v67, v60, v61
	v_lshlrev_b32_e32 v60, 16, v38
	v_lshlrev_b32_e32 v61, 16, v42
	v_pk_mov_b32 v[62:63], v[68:69], v[60:61] op_sel:[1,0]
	s_nop 0
	v_pk_mul_f32 v[64:65], v[98:99], v[62:63]
	s_nop 0
	v_add_f32_e32 v64, v66, v64
	v_add_f32_e32 v71, v64, v65
	v_pk_mul_f32 v[64:65], v[98:99], v[60:61]
	s_nop 0
	v_add_f32_e32 v64, v67, v64
	v_add_f32_e32 v87, v64, v65
	v_pk_mul_f32 v[64:65], v[0:1], v[72:73]
	s_nop 0
	v_add_f32_e32 v64, v9, v64
	v_add_f32_e32 v75, v64, v65
	v_and_b32_e32 v65, 0xffff0000, v42
	v_and_b32_e32 v64, 0xffff0000, v38
	v_pk_mov_b32 v[66:67], v[72:73], v[64:65] op_sel:[1,0]
	s_nop 0
	v_pk_mul_f32 v[68:69], v[4:5], v[66:67]
	s_nop 0
	v_add_f32_e32 v38, v70, v68
	v_add_f32_e32 v38, v38, v69
	v_pk_mul_f32 v[68:69], v[4:5], v[64:65]
	v_cvt_pk_bf16_f32 v38, v71, v38
	s_nop 0
	v_add_f32_e32 v42, v75, v68
	v_add_f32_e32 v88, v42, v69
	v_pk_mul_f32 v[68:69], v[76:77], v[78:79]
	s_nop 0
	v_add_f32_e32 v42, v10, v68
	v_add_f32_e32 v42, v42, v69
	v_lshlrev_b32_e32 v68, 16, v39
	v_lshlrev_b32_e32 v69, 16, v43
	v_pk_mov_b32 v[70:71], v[78:79], v[68:69] op_sel:[1,0]
	v_and_b32_e32 v43, 0xffff0000, v43
	v_pk_mul_f32 v[72:73], v[80:81], v[70:71]
	s_nop 0
	v_add_f32_e32 v72, v74, v72
	v_add_f32_e32 v89, v72, v73
	v_pk_mul_f32 v[72:73], v[80:81], v[68:69]
	s_nop 0
	v_add_f32_e32 v72, v42, v72
	v_and_b32_e32 v42, 0xffff0000, v39
	v_pk_mov_b32 v[74:75], v[50:51], v[42:43] op_sel:[1,0]
	v_pk_mul_f32 v[50:51], v[2:3], v[50:51]
	v_pk_mul_f32 v[78:79], v[6:7], v[74:75]
	v_add_f32_e32 v50, v11, v50
	v_add_f32_e32 v39, v82, v78
	v_add_f32_e32 v39, v39, v79
	v_mov_b32_e32 v78, s0
	v_mov_b32_e32 v79, s1
	v_cvt_pk_bf16_f32 v39, v89, v39
	v_add_f32_e32 v72, v72, v73
	v_readfirstlane_b32 s16, v78
	v_readfirstlane_b32 s17, v79
	s_load_dwordx2 s[16:17], s[16:17], 0xc0
	v_add_f32_e32 v73, v50, v51
	s_waitcnt lgkmcnt(0)
	v_mov_b64_e32 v[50:51], s[16:17]
	v_mad_i64_i32 v[50:51], s[16:17], v139, s24, v[50:51]
	v_lshl_add_u64 v[50:51], v[50:51], 0, v[110:111]
	v_add_co_u32_e32 v50, vcc, s26, v50
	s_nop 1
	v_addc_co_u32_e32 v51, vcc, 0, v51, vcc
	global_store_dwordx4 v[50:51], v[36:39], off sc1
	v_mov_b32_e32 v50, s0
	v_mov_b32_e32 v51, s1
	v_pk_mul_f32 v[36:37], v[6:7], v[42:43]
	s_nop 0
	v_add_f32_e32 v36, v73, v36
	v_add_f32_e32 v39, v36, v37
	v_cvt_pk_bf16_f32 v36, v83, v84
	v_cvt_pk_bf16_f32 v37, v85, v86
	v_cvt_pk_bf16_f32 v38, v87, v88
	v_cvt_pk_bf16_f32 v39, v72, v39
	s_nop 0
	v_readfirstlane_b32 s16, v50
	v_readfirstlane_b32 s17, v51
	s_load_dwordx2 s[16:17], s[16:17], 0xc0
	s_waitcnt lgkmcnt(0)
	v_mov_b64_e32 v[50:51], s[16:17]
	v_mad_i64_i32 v[50:51], s[16:17], v138, s24, v[50:51]
	v_lshl_add_u64 v[50:51], v[50:51], 0, v[110:111]
	v_add_co_u32_e32 v50, vcc, s26, v50
	s_nop 1
	v_addc_co_u32_e32 v51, vcc, 0, v51, vcc
	global_store_dwordx4 v[50:51], v[36:39], off sc1
	s_nop 1
	v_pk_mul_f32 v[36:37], v[112:113], v[46:47]
	s_nop 0
	v_add_f32_e32 v36, v20, v36
	v_add_f32_e32 v46, v36, v37
	v_pk_mul_f32 v[36:37], v[12:13], v[54:55]
	s_nop 0
	v_add_f32_e32 v36, v21, v36
	v_add_f32_e32 v50, v36, v37
	v_pk_mul_f32 v[36:37], v[92:93], v[58:59]
	s_nop 0
	v_add_f32_e32 v36, v22, v36
	v_add_f32_e32 v54, v36, v37
	v_pk_mul_f32 v[36:37], v[14:15], v[48:49]
	s_nop 0
	v_add_f32_e32 v36, v23, v36
	v_add_f32_e32 v55, v36, v37
	v_pk_mul_f32 v[36:37], v[94:95], v[62:63]
	s_nop 0
	v_add_f32_e32 v36, v8, v36
	v_add_f32_e32 v58, v36, v37
	v_pk_mul_f32 v[36:37], v[0:1], v[66:67]
	s_nop 0
	v_add_f32_e32 v36, v9, v36
	v_add_f32_e32 v62, v36, v37
	v_pk_mul_f32 v[36:37], v[76:77], v[70:71]
	s_nop 0
	v_add_f32_e32 v36, v10, v36
	v_add_f32_e32 v66, v36, v37
	v_pk_mul_f32 v[36:37], v[2:3], v[74:75]
	s_nop 0
	v_add_f32_e32 v36, v11, v36
	v_add_f32_e32 v70, v36, v37
	v_pk_mul_f32 v[36:37], v[112:113], v[44:45]
	s_nop 0
	v_add_f32_e32 v36, v20, v36
	v_add_f32_e32 v47, v36, v37
	s_waitcnt vmcnt(15)
	v_lshlrev_b32_e32 v36, 16, v28
	s_waitcnt vmcnt(14)
	v_lshlrev_b32_e32 v37, 16, v32
	v_pk_mov_b32 v[38:39], v[44:45], v[36:37] op_sel:[1,0]
	s_nop 0
	v_pk_mul_f32 v[44:45], v[114:115], v[38:39]
	v_pk_mul_f32 v[38:39], v[112:113], v[38:39]
	v_add_f32_e32 v44, v46, v44
	v_add_f32_e32 v51, v44, v45
	v_pk_mul_f32 v[44:45], v[114:115], v[36:37]
	v_add_f32_e32 v20, v20, v38
	v_add_f32_e32 v36, v47, v44
	v_add_f32_e32 v36, v36, v45
	v_pk_mul_f32 v[44:45], v[12:13], v[52:53]
	v_add_f32_e32 v20, v20, v39
	v_add_f32_e32 v44, v21, v44
	v_add_f32_e32 v59, v44, v45
	v_and_b32_e32 v45, 0xffff0000, v32
	v_and_b32_e32 v44, 0xffff0000, v28
	v_pk_mov_b32 v[46:47], v[52:53], v[44:45] op_sel:[1,0]
	s_nop 0
	v_pk_mul_f32 v[48:49], v[16:17], v[46:47]
	v_pk_mul_f32 v[12:13], v[12:13], v[46:47]
	v_add_f32_e32 v28, v50, v48
	v_add_f32_e32 v28, v28, v49
	v_pk_mul_f32 v[48:49], v[16:17], v[44:45]
	v_cvt_pk_bf16_f32 v28, v51, v28
	v_add_f32_e32 v12, v21, v12
	v_add_f32_e32 v32, v59, v48
	v_add_f32_e32 v44, v32, v49
	v_pk_mul_f32 v[48:49], v[92:93], v[56:57]
	v_add_f32_e32 v21, v12, v13
	v_add_f32_e32 v32, v22, v48
	v_add_f32_e32 v32, v32, v49
	v_lshlrev_b32_e32 v48, 16, v29
	v_lshlrev_b32_e32 v49, 16, v33
	v_pk_mov_b32 v[50:51], v[56:57], v[48:49] op_sel:[1,0]
	v_and_b32_e32 v33, 0xffff0000, v33
	v_pk_mul_f32 v[52:53], v[96:97], v[50:51]
	s_nop 0
	v_add_f32_e32 v52, v54, v52
	v_add_f32_e32 v54, v52, v53
	v_pk_mul_f32 v[52:53], v[96:97], v[48:49]
	s_nop 0
	v_add_f32_e32 v32, v32, v52
	v_add_f32_e32 v48, v32, v53
	v_pk_mul_f32 v[52:53], v[14:15], v[40:41]
	s_nop 0
	v_add_f32_e32 v32, v23, v52
	v_add_f32_e32 v56, v32, v53
	v_and_b32_e32 v32, 0xffff0000, v29
	v_pk_mov_b32 v[40:41], v[40:41], v[32:33] op_sel:[1,0]
	s_nop 0
	v_pk_mul_f32 v[52:53], v[18:19], v[40:41]
	s_nop 0
	v_add_f32_e32 v29, v55, v52
	v_add_f32_e32 v29, v29, v53
	v_pk_mul_f32 v[52:53], v[18:19], v[32:33]
	v_cvt_pk_bf16_f32 v29, v54, v29
	s_nop 0
	v_add_f32_e32 v32, v56, v52
	v_add_f32_e32 v32, v32, v53
	v_pk_mul_f32 v[52:53], v[94:95], v[60:61]
	s_nop 0
	v_add_f32_e32 v52, v8, v52
	v_add_f32_e32 v59, v52, v53
	v_lshlrev_b32_e32 v52, 16, v30
	v_lshlrev_b32_e32 v53, 16, v34
	v_pk_mov_b32 v[54:55], v[60:61], v[52:53] op_sel:[1,0]
	s_nop 0
	v_pk_mul_f32 v[56:57], v[98:99], v[54:55]
	s_nop 0
	v_add_f32_e32 v56, v58, v56
	v_add_f32_e32 v63, v56, v57
	v_pk_mul_f32 v[56:57], v[98:99], v[52:53]
	s_nop 0
	v_add_f32_e32 v52, v59, v56
	v_add_f32_e32 v52, v52, v57
	v_pk_mul_f32 v[56:57], v[0:1], v[64:65]
	s_nop 0
	v_add_f32_e32 v56, v9, v56
	v_add_f32_e32 v67, v56, v57
	v_and_b32_e32 v57, 0xffff0000, v34
	v_and_b32_e32 v56, 0xffff0000, v30
	v_pk_mov_b32 v[58:59], v[64:65], v[56:57] op_sel:[1,0]
	s_nop 0
	v_pk_mul_f32 v[60:61], v[4:5], v[58:59]
	v_pk_mul_f32 v[0:1], v[0:1], v[58:59]
	v_add_f32_e32 v30, v62, v60
	v_add_f32_e32 v30, v30, v61
	v_pk_mul_f32 v[60:61], v[4:5], v[56:57]
	v_cvt_pk_bf16_f32 v30, v63, v30
	v_add_f32_e32 v0, v9, v0
	v_add_f32_e32 v34, v67, v60
	v_add_f32_e32 v56, v34, v61
	v_pk_mul_f32 v[60:61], v[76:77], v[68:69]
	v_add_f32_e32 v9, v0, v1
	v_add_f32_e32 v34, v10, v60
	v_add_f32_e32 v34, v34, v61
	v_lshlrev_b32_e32 v60, 16, v31
	v_lshlrev_b32_e32 v61, 16, v35
	v_pk_mov_b32 v[62:63], v[68:69], v[60:61] op_sel:[1,0]
	v_and_b32_e32 v35, 0xffff0000, v35
	v_pk_mul_f32 v[64:65], v[80:81], v[62:63]
	s_nop 0
	v_add_f32_e32 v64, v66, v64
	v_add_f32_e32 v71, v64, v65
	v_pk_mul_f32 v[64:65], v[80:81], v[60:61]
	s_nop 0
	v_add_f32_e32 v60, v34, v64
	v_and_b32_e32 v34, 0xffff0000, v31
	v_pk_mov_b32 v[66:67], v[42:43], v[34:35] op_sel:[1,0]
	v_mov_b32_e32 v64, s0
	v_pk_mul_f32 v[68:69], v[6:7], v[66:67]
	v_pk_mul_f32 v[42:43], v[2:3], v[42:43]
	v_add_f32_e32 v31, v70, v68
	v_add_f32_e32 v31, v31, v69
	v_mov_b32_e32 v68, s1
	v_cvt_pk_bf16_f32 v31, v71, v31
	v_add_f32_e32 v42, v11, v42
	v_readfirstlane_b32 s16, v64
	v_readfirstlane_b32 s17, v68
	s_load_dwordx2 s[16:17], s[16:17], 0xc0
	v_add_f32_e32 v64, v42, v43
	v_add_f32_e32 v60, v60, v65
	s_waitcnt vmcnt(13)
	v_and_b32_e32 v69, 0xffff0000, v26
	v_mov_b32_e32 v68, v57
	s_waitcnt lgkmcnt(0)
	v_mov_b64_e32 v[42:43], s[16:17]
	v_mad_i64_i32 v[42:43], s[16:17], v137, s24, v[42:43]
	v_lshl_add_u64 v[42:43], v[42:43], 0, v[110:111]
	v_add_co_u32_e32 v42, vcc, s26, v42
	v_pk_mul_f32 v[0:1], v[4:5], v[68:69]
	s_nop 0
	v_addc_co_u32_e32 v43, vcc, 0, v43, vcc
	global_store_dwordx4 v[42:43], v[28:31], off sc1
	v_add_f32_e32 v0, v9, v0
	v_add_f32_e32 v4, v0, v1
	v_pk_mul_f32 v[28:29], v[6:7], v[34:35]
	v_mov_b32_e32 v34, s1
	v_add_f32_e32 v28, v64, v28
	v_add_f32_e32 v31, v28, v29
	v_cvt_pk_bf16_f32 v28, v36, v44
	v_cvt_pk_bf16_f32 v29, v48, v32
	v_mov_b32_e32 v32, s0
	v_cvt_pk_bf16_f32 v30, v52, v56
	v_cvt_pk_bf16_f32 v31, v60, v31
	v_pk_mul_f32 v[0:1], v[76:77], v[62:63]
	v_readfirstlane_b32 s16, v32
	v_readfirstlane_b32 s17, v34
	s_load_dwordx2 s[16:17], s[16:17], 0xc0
	v_lshlrev_b32_e32 v71, 16, v27
	v_add_f32_e32 v0, v10, v0
	v_mov_b32_e32 v70, v61
	v_add_f32_e32 v5, v0, v1
	s_waitcnt lgkmcnt(0)
	v_mov_b64_e32 v[42:43], s[16:17]
	v_mad_i64_i32 v[42:43], s[16:17], v136, s24, v[42:43]
	v_lshl_add_u64 v[42:43], v[42:43], 0, v[110:111]
	v_add_co_u32_e32 v42, vcc, s26, v42
	v_pk_mul_f32 v[0:1], v[80:81], v[70:71]
	s_nop 0
	v_addc_co_u32_e32 v43, vcc, 0, v43, vcc
	global_store_dwordx4 v[42:43], v[28:31], off sc1
	v_lshlrev_b32_e32 v43, 16, v25
	v_mov_b32_e32 v42, v49
	v_and_b32_e32 v31, 0xffff0000, v24
	v_mov_b32_e32 v30, v45
	v_pk_mul_f32 v[12:13], v[16:17], v[30:31]
	v_lshlrev_b32_e32 v29, 16, v24
	v_add_f32_e32 v12, v21, v12
	v_add_f32_e32 v16, v12, v13
	v_pk_mul_f32 v[12:13], v[92:93], v[50:51]
	v_and_b32_e32 v25, 0xffff0000, v25
	v_add_f32_e32 v12, v22, v12
	v_add_f32_e32 v17, v12, v13
	v_pk_mul_f32 v[12:13], v[96:97], v[42:43]
	v_mov_b32_e32 v24, v33
	v_add_f32_e32 v12, v17, v12
	v_add_f32_e32 v17, v12, v13
	v_pk_mul_f32 v[12:13], v[14:15], v[40:41]
	v_add_f32_e32 v0, v5, v0
	v_add_f32_e32 v12, v23, v12
	v_add_f32_e32 v14, v12, v13
	v_pk_mul_f32 v[12:13], v[18:19], v[24:25]
	v_add_f32_e32 v5, v0, v1
	v_add_f32_e32 v12, v14, v12
	v_pk_mul_f32 v[0:1], v[2:3], v[66:67]
	v_lshlrev_b32_e32 v65, 16, v26
	v_and_b32_e32 v27, 0xffff0000, v27
	v_add_f32_e32 v14, v12, v13
	v_pk_mul_f32 v[12:13], v[94:95], v[54:55]
	v_add_f32_e32 v0, v11, v0
	v_mov_b32_e32 v26, v35
	v_mov_b32_e32 v28, v37
	v_add_f32_e32 v8, v8, v12
	v_mov_b32_e32 v64, v53
	v_add_f32_e32 v2, v0, v1
	v_pk_mul_f32 v[0:1], v[6:7], v[26:27]
	v_pk_mul_f32 v[28:29], v[114:115], v[28:29]
	v_add_f32_e32 v8, v8, v13
	v_pk_mul_f32 v[12:13], v[98:99], v[64:65]
	v_add_f32_e32 v0, v2, v0
	v_add_f32_e32 v20, v20, v28
	v_add_f32_e32 v8, v8, v12
	v_add_f32_e32 v3, v0, v1
	v_add_f32_e32 v20, v20, v29
	v_add_f32_e32 v8, v8, v13
	v_cvt_pk_bf16_f32 v0, v20, v16
	v_cvt_pk_bf16_f32 v1, v17, v14
	v_cvt_pk_bf16_f32 v2, v8, v4
	v_cvt_pk_bf16_f32 v3, v5, v3
	s_nop 0
	v_readfirstlane_b32 s16, v133
	v_readfirstlane_b32 s17, v134
	s_load_dwordx2 s[16:17], s[16:17], 0xc0
	s_waitcnt lgkmcnt(0)
	v_mov_b64_e32 v[4:5], s[16:17]
	v_mad_i64_i32 v[4:5], s[16:17], v135, s24, v[4:5]
	v_lshl_add_u64 v[4:5], v[4:5], 0, v[110:111]
	v_add_co_u32_e32 v4, vcc, 0x14000000, v4
	s_nop 1
	v_addc_co_u32_e32 v5, vcc, 0, v5, vcc
	v_cmp_lt_i32_e32 vcc, s27, v109
	s_or_b64 s[10:11], vcc, s[10:11]
	global_store_dwordx4 v[4:5], v[0:3], off sc1
	s_andn2_b64 exec, exec, s[10:11]
	s_cbranch_execz .LBB0_487

.LBB0_493:
	global_load_dwordx4 v[8:11], v[4:5], off
	v_add_u32_e32 v7, 0x200, v7
	v_cmp_lt_u32_e32 vcc, s23, v7
	v_lshl_add_u64 v[4:5], v[4:5], 0, s[10:11]
	s_or_b64 s[14:15], vcc, s[14:15]
	s_waitcnt vmcnt(0)
	ds_write2_b64 v6, v[8:9], v[10:11] offset1:1
	v_add_u32_e32 v6, 0x2080, v6
	s_andn2_b64 exec, exec, s[14:15]
	s_cbranch_execnz .LBB0_493
	s_or_b64 exec, exec, s[14:15]
	s_waitcnt lgkmcnt(0)
	s_barrier
	ds_read_b128 v[4:7], v159
	ds_read_b128 v[8:11], v159 offset:32
	s_waitcnt lgkmcnt(1)
	v_mfma_f32_32x32x16_bf16 v[112:127], v[4:7], v[0:3], 0
	s_lshl_b32 s4, s26, 8
	s_and_b32 s19, s4, 0xf00
	s_add_i32 s18, s26, s33
	s_cmpk_lt_i32 s18, 0x200
	s_cselect_b64 s[14:15], -1, 0
	s_and_b64 s[28:29], s[14:15], exec
	s_cselect_b32 s4, s18, s26
	s_waitcnt lgkmcnt(0)
	v_mfma_f32_32x32x16_bf16 v[112:127], v[8:11], v[136:139], v[112:127]
	ds_read_b128 v[4:7], v159 offset:64
	ds_read_b128 v[8:11], v159 offset:96
	s_ashr_i32 s28, s4, 6
	s_ashr_i32 s29, s28, 31
	s_lshl_b32 s27, s4, 8
	s_and_b32 s27, s27, 0xf00
	s_lshl_b64 s[28:29], s[28:29], 21
	s_add_u32 s28, s3, s28
	s_waitcnt lgkmcnt(1)
	v_mfma_f32_32x32x16_bf16 v[112:127], v[4:7], v[132:135], v[112:127]
	s_addc_u32 s29, s20, s29
	v_add_lshl_u32 v140, s27, v154, 9
	v_lshl_add_u64 v[190:191], s[28:29], 0, v[140:141]
	s_lshl_b32 s4, s4, 3
	s_and_b32 s4, s4, 0x180
	s_lshl_b64 s[16:17], s[16:17], 23
	s_add_u32 s16, s6, s16
	s_waitcnt lgkmcnt(0)
	v_mfma_f32_32x32x16_bf16 v[112:127], v[8:11], v[128:131], v[112:127]
	ds_read_b128 v[4:7], v160
	ds_read_b128 v[8:11], v160 offset:32
	s_addc_u32 s17, s7, s17
	s_add_i32 s21, s21, s22
	s_waitcnt lgkmcnt(1)
	v_mfma_f32_32x32x16_bf16 v[96:111], v[4:7], v[0:3], 0
	s_waitcnt lgkmcnt(0)
	v_mfma_f32_32x32x16_bf16 v[96:111], v[8:11], v[136:139], v[96:111]
	ds_read_b128 v[4:7], v160 offset:64
	ds_read_b128 v[8:11], v160 offset:96
	s_waitcnt lgkmcnt(1)
	v_mfma_f32_32x32x16_bf16 v[96:111], v[4:7], v[132:135], v[96:111]
	s_waitcnt lgkmcnt(0)
	v_mfma_f32_32x32x16_bf16 v[96:111], v[8:11], v[128:131], v[96:111]
	ds_read_b128 v[4:7], v159 offset:9216
	ds_read_b128 v[8:11], v159 offset:9248
	s_waitcnt lgkmcnt(1)
	v_mfma_f32_32x32x16_bf16 v[80:95], v[4:7], v[0:3], 0
	s_waitcnt lgkmcnt(0)
	v_mfma_f32_32x32x16_bf16 v[80:95], v[8:11], v[136:139], v[80:95]
	ds_read_b128 v[4:7], v159 offset:9280
	ds_read_b128 v[8:11], v159 offset:9312
	s_waitcnt lgkmcnt(1)
	v_mfma_f32_32x32x16_bf16 v[80:95], v[4:7], v[132:135], v[80:95]
	s_waitcnt lgkmcnt(0)
	v_mfma_f32_32x32x16_bf16 v[80:95], v[8:11], v[128:131], v[80:95]
	ds_read_b128 v[4:7], v161
	ds_read_b128 v[8:11], v161 offset:32
	s_waitcnt lgkmcnt(1)
	v_mfma_f32_32x32x16_bf16 v[64:79], v[4:7], v[0:3], 0
	s_waitcnt lgkmcnt(0)
	v_mfma_f32_32x32x16_bf16 v[64:79], v[8:11], v[136:139], v[64:79]
	ds_read_b128 v[4:7], v161 offset:64
	ds_read_b128 v[8:11], v161 offset:96
	s_waitcnt lgkmcnt(1)
	v_mfma_f32_32x32x16_bf16 v[64:79], v[4:7], v[132:135], v[64:79]
	s_waitcnt lgkmcnt(0)
	v_mfma_f32_32x32x16_bf16 v[64:79], v[8:11], v[128:131], v[64:79]
	ds_read_b128 v[4:7], v159 offset:18432
	ds_read_b128 v[8:11], v159 offset:18464
	s_waitcnt lgkmcnt(1)
	v_mfma_f32_32x32x16_bf16 v[48:63], v[4:7], v[0:3], 0
	s_waitcnt lgkmcnt(0)
	v_mfma_f32_32x32x16_bf16 v[48:63], v[8:11], v[136:139], v[48:63]
	ds_read_b128 v[4:7], v159 offset:18496
	ds_read_b128 v[8:11], v159 offset:18528
	s_waitcnt lgkmcnt(1)
	v_mfma_f32_32x32x16_bf16 v[48:63], v[4:7], v[132:135], v[48:63]
	ds_read_b128 v[4:7], v162
	s_waitcnt lgkmcnt(1)
	v_mfma_f32_32x32x16_bf16 v[48:63], v[8:11], v[128:131], v[48:63]
	ds_read_b128 v[8:11], v162 offset:32
	s_waitcnt lgkmcnt(1)
	v_mfma_f32_32x32x16_bf16 v[32:47], v[4:7], v[0:3], 0
	ds_read_b128 v[4:7], v162 offset:64
	s_waitcnt lgkmcnt(1)
	v_mfma_f32_32x32x16_bf16 v[32:47], v[8:11], v[136:139], v[32:47]
	ds_read_b128 v[8:11], v162 offset:96
	s_waitcnt lgkmcnt(1)
	v_mfma_f32_32x32x16_bf16 v[32:47], v[4:7], v[132:135], v[32:47]
	ds_read_b128 v[4:7], v159 offset:27648
	ds_read_b128 v[12:15], v159 offset:27680
	ds_read_b128 v[166:169], v159 offset:27712
	ds_read_b128 v[170:173], v159 offset:27744
	ds_read_b128 v[174:177], v163
	ds_read_b128 v[178:181], v163 offset:32
	ds_read_b128 v[182:185], v163 offset:64
	ds_read_b128 v[186:189], v163 offset:96
	s_waitcnt lgkmcnt(8)
	v_mfma_f32_32x32x16_bf16 v[32:47], v[8:11], v[128:131], v[32:47]
	v_max3_f32 v8, v112, s24, v113
	v_max3_f32 v8, v8, v114, v115
	v_max3_f32 v8, v8, v116, v117
	v_max3_f32 v8, v8, v118, v119
	v_max3_f32 v8, v8, v120, v121
	v_max3_f32 v8, v8, v122, v123
	v_max3_f32 v8, v8, v124, v125
	s_waitcnt lgkmcnt(7)
	v_mfma_f32_32x32x16_bf16 v[16:31], v[4:7], v[0:3], 0
	v_max3_f32 v4, v8, v126, v127
	v_max3_f32 v4, v4, v96, v97
	v_max3_f32 v4, v4, v98, v99
	v_max3_f32 v4, v4, v100, v101
	v_max3_f32 v4, v4, v102, v103
	v_max3_f32 v4, v4, v104, v105
	v_max3_f32 v4, v4, v106, v107
	v_max3_f32 v4, v4, v108, v109
	v_max3_f32 v4, v4, v110, v111
	v_max3_f32 v4, v4, v80, v81
	v_max3_f32 v4, v4, v82, v83
	v_max3_f32 v4, v4, v84, v85
	v_max3_f32 v4, v4, v86, v87
	v_max3_f32 v4, v4, v88, v89
	v_max3_f32 v4, v4, v90, v91
	v_max3_f32 v4, v4, v92, v93
	v_max3_f32 v4, v4, v94, v95
	v_max3_f32 v4, v4, v64, v65
	v_max3_f32 v4, v4, v66, v67
	v_max3_f32 v4, v4, v68, v69
	v_max3_f32 v4, v4, v70, v71
	v_max3_f32 v4, v4, v72, v73
	v_max3_f32 v4, v4, v74, v75
	v_max3_f32 v4, v4, v76, v77
	v_max3_f32 v4, v4, v78, v79
	v_max3_f32 v4, v4, v48, v49
	v_max3_f32 v4, v4, v50, v51
	s_waitcnt lgkmcnt(6)
	v_mfma_f32_32x32x16_bf16 v[16:31], v[12:15], v[136:139], v[16:31]
	v_max3_f32 v140, v4, v52, v53
	v_max3_f32 v140, v140, v54, v55
	v_max3_f32 v140, v140, v56, v57
	v_max3_f32 v140, v140, v58, v59
	v_max3_f32 v140, v140, v60, v61
	v_max3_f32 v140, v140, v62, v63
	v_max3_f32 v140, v140, v32, v33
	s_waitcnt lgkmcnt(3)
	v_mfma_f32_32x32x16_bf16 v[0:15], v[174:177], v[0:3], 0
	v_max3_f32 v140, v140, v34, v35
	v_mfma_f32_32x32x16_bf16 v[16:31], v[166:169], v[132:135], v[16:31]
	s_waitcnt lgkmcnt(2)
	v_mfma_f32_32x32x16_bf16 v[0:15], v[178:181], v[136:139], v[0:15]
	v_max3_f32 v136, v140, v36, v37
	v_max3_f32 v136, v136, v38, v39
	v_max3_f32 v136, v136, v40, v41
	v_max3_f32 v136, v136, v42, v43
	v_max3_f32 v136, v136, v44, v45
	v_max3_f32 v136, v136, v46, v47
	v_add_lshl_u32 v140, s19, v154, 11
	v_mfma_f32_32x32x16_bf16 v[16:31], v[170:173], v[128:131], v[16:31]
	s_waitcnt lgkmcnt(1)
	v_mfma_f32_32x32x16_bf16 v[0:15], v[182:185], v[132:135], v[0:15]
	s_nop 9
	v_max3_f32 v136, v136, v16, v17
	v_max3_f32 v132, v136, v18, v19
	v_max3_f32 v132, v132, v20, v21
	v_max3_f32 v132, v132, v22, v23
	v_max3_f32 v132, v132, v24, v25
	v_max3_f32 v132, v132, v26, v27
	v_max3_f32 v132, v132, v28, v29
	s_waitcnt lgkmcnt(0)
	v_mfma_f32_32x32x16_bf16 v[0:15], v[186:189], v[128:131], v[0:15]
	v_max3_f32 v132, v132, v30, v31
	s_nop 10
	v_max3_f32 v128, v132, v0, v1
	v_max3_f32 v128, v128, v2, v3
	v_max3_f32 v128, v128, v4, v5
	v_max3_f32 v128, v128, v6, v7
	v_max3_f32 v128, v128, v8, v9
	v_max3_f32 v128, v128, v10, v11
	v_max3_f32 v128, v128, v12, v13
	v_max3_f32 v130, v128, v14, v15
	ds_bpermute_b32 v131, v155, v130
	v_lshl_add_u64 v[128:129], v[190:191], 0, s[4:5]
	s_lshl_b32 s4, s26, 3
	s_and_b32 s4, s4, 0x180
	s_mov_b32 s26, s18
	s_waitcnt lgkmcnt(0)
	v_max_f32_e32 v131, v131, v131
	v_max_f32_e32 v130, v130, v131
	v_sub_f32_e32 v112, v112, v130
	v_exp_f32_e32 v112, v112
	v_sub_f32_e32 v113, v113, v130
	v_exp_f32_e32 v113, v113
	v_sub_f32_e32 v114, v114, v130
	v_exp_f32_e32 v114, v114
	v_sub_f32_e32 v115, v115, v130
	v_exp_f32_e32 v115, v115
	v_sub_f32_e32 v116, v116, v130
	v_add_f32_e32 v131, 0, v112
	v_exp_f32_e32 v116, v116
	v_sub_f32_e32 v117, v117, v130
	v_add_f32_e32 v131, v113, v131
	v_exp_f32_e32 v117, v117
	v_sub_f32_e32 v118, v118, v130
	v_add_f32_e32 v131, v114, v131
	v_exp_f32_e32 v118, v118
	v_sub_f32_e32 v119, v119, v130
	v_add_f32_e32 v131, v115, v131
	v_exp_f32_e32 v119, v119
	v_sub_f32_e32 v120, v120, v130
	v_add_f32_e32 v131, v116, v131
	v_exp_f32_e32 v120, v120
	v_sub_f32_e32 v121, v121, v130
	v_add_f32_e32 v131, v117, v131
	v_exp_f32_e32 v121, v121
	v_sub_f32_e32 v122, v122, v130
	v_add_f32_e32 v131, v118, v131
	v_exp_f32_e32 v122, v122
	v_sub_f32_e32 v123, v123, v130
	v_add_f32_e32 v131, v119, v131
	v_exp_f32_e32 v123, v123
	v_sub_f32_e32 v124, v124, v130
	v_add_f32_e32 v131, v120, v131
	v_exp_f32_e32 v124, v124
	v_sub_f32_e32 v125, v125, v130
	v_add_f32_e32 v131, v121, v131
	v_exp_f32_e32 v125, v125
	v_sub_f32_e32 v126, v126, v130
	v_add_f32_e32 v131, v122, v131
	v_exp_f32_e32 v126, v126
	v_sub_f32_e32 v127, v127, v130
	v_add_f32_e32 v131, v123, v131
	v_exp_f32_e32 v127, v127
	v_sub_f32_e32 v96, v96, v130
	v_add_f32_e32 v131, v124, v131
	v_exp_f32_e32 v96, v96
	v_sub_f32_e32 v97, v97, v130
	v_add_f32_e32 v131, v125, v131
	v_exp_f32_e32 v97, v97
	v_sub_f32_e32 v98, v98, v130
	v_add_f32_e32 v131, v126, v131
	v_exp_f32_e32 v98, v98
	v_sub_f32_e32 v99, v99, v130
	v_add_f32_e32 v131, v127, v131
	v_exp_f32_e32 v99, v99
	v_sub_f32_e32 v100, v100, v130
	v_add_f32_e32 v131, v96, v131
	v_exp_f32_e32 v100, v100
	v_sub_f32_e32 v101, v101, v130
	v_add_f32_e32 v131, v97, v131
	v_exp_f32_e32 v101, v101
	v_sub_f32_e32 v102, v102, v130
	v_add_f32_e32 v131, v98, v131
	v_exp_f32_e32 v102, v102
	v_sub_f32_e32 v103, v103, v130
	v_add_f32_e32 v131, v99, v131
	v_exp_f32_e32 v103, v103
	v_sub_f32_e32 v104, v104, v130
	v_add_f32_e32 v131, v100, v131
	v_exp_f32_e32 v104, v104
	v_sub_f32_e32 v105, v105, v130
	v_add_f32_e32 v131, v101, v131
	v_exp_f32_e32 v105, v105
	v_sub_f32_e32 v106, v106, v130
	v_add_f32_e32 v131, v102, v131
	v_exp_f32_e32 v106, v106
	v_sub_f32_e32 v107, v107, v130
	v_add_f32_e32 v131, v103, v131
	v_exp_f32_e32 v107, v107
	v_sub_f32_e32 v108, v108, v130
	v_add_f32_e32 v131, v104, v131
	v_exp_f32_e32 v108, v108
	v_sub_f32_e32 v109, v109, v130
	v_add_f32_e32 v131, v105, v131
	v_exp_f32_e32 v109, v109
	v_sub_f32_e32 v110, v110, v130
	v_add_f32_e32 v131, v106, v131
	v_exp_f32_e32 v110, v110
	v_sub_f32_e32 v111, v111, v130
	v_add_f32_e32 v131, v107, v131
	v_exp_f32_e32 v111, v111
	v_sub_f32_e32 v80, v80, v130
	v_add_f32_e32 v131, v108, v131
	v_exp_f32_e32 v132, v80
	v_sub_f32_e32 v80, v81, v130
	v_add_f32_e32 v131, v109, v131
	v_exp_f32_e32 v133, v80
	v_sub_f32_e32 v80, v82, v130
	v_add_f32_e32 v131, v110, v131
	v_exp_f32_e32 v134, v80
	v_sub_f32_e32 v81, v83, v130
	v_add_f32_e32 v80, v111, v131
	v_exp_f32_e32 v131, v81
	v_sub_f32_e32 v81, v84, v130
	v_add_f32_e32 v80, v132, v80
	v_exp_f32_e32 v135, v81
	v_sub_f32_e32 v81, v85, v130
	v_add_f32_e32 v80, v133, v80
	v_exp_f32_e32 v136, v81
	v_sub_f32_e32 v81, v86, v130
	v_add_f32_e32 v80, v134, v80
	v_exp_f32_e32 v137, v81
	v_sub_f32_e32 v81, v87, v130
	v_add_f32_e32 v80, v131, v80
	v_exp_f32_e32 v138, v81
	v_sub_f32_e32 v81, v88, v130
	v_add_f32_e32 v80, v135, v80
	v_exp_f32_e32 v88, v81
	v_sub_f32_e32 v81, v89, v130
	v_add_f32_e32 v80, v136, v80
	v_exp_f32_e32 v89, v81
	v_sub_f32_e32 v81, v90, v130
	v_add_f32_e32 v80, v137, v80
	v_exp_f32_e32 v90, v81
	v_sub_f32_e32 v81, v91, v130
	v_add_f32_e32 v80, v138, v80
	v_exp_f32_e32 v91, v81
	v_sub_f32_e32 v81, v92, v130
	v_add_f32_e32 v80, v88, v80
	v_exp_f32_e32 v92, v81
	v_sub_f32_e32 v81, v93, v130
	v_add_f32_e32 v80, v89, v80
	v_exp_f32_e32 v93, v81
	v_sub_f32_e32 v81, v94, v130
	v_add_f32_e32 v80, v90, v80
	v_exp_f32_e32 v94, v81
	v_sub_f32_e32 v81, v95, v130
	v_add_f32_e32 v80, v91, v80
	v_exp_f32_e32 v95, v81
	v_sub_f32_e32 v64, v64, v130
	v_add_f32_e32 v80, v92, v80
	v_exp_f32_e32 v139, v64
	v_sub_f32_e32 v64, v65, v130
	v_add_f32_e32 v80, v93, v80
	v_exp_f32_e32 v147, v64
	v_sub_f32_e32 v64, v66, v130
	v_add_f32_e32 v80, v94, v80
	v_exp_f32_e32 v149, v64
	v_sub_f32_e32 v65, v67, v130
	v_add_f32_e32 v64, v95, v80
	v_exp_f32_e32 v151, v65
	v_sub_f32_e32 v65, v68, v130
	v_add_f32_e32 v64, v139, v64
	v_exp_f32_e32 v153, v65
	v_sub_f32_e32 v65, v69, v130
	v_add_f32_e32 v64, v147, v64
	v_exp_f32_e32 v166, v65
	v_sub_f32_e32 v65, v70, v130
	v_add_f32_e32 v64, v149, v64
	v_exp_f32_e32 v167, v65
	v_sub_f32_e32 v65, v71, v130
	v_add_f32_e32 v64, v151, v64
	v_exp_f32_e32 v168, v65
	v_sub_f32_e32 v65, v72, v130
	v_add_f32_e32 v64, v153, v64
	v_exp_f32_e32 v169, v65
	v_sub_f32_e32 v65, v73, v130
	v_add_f32_e32 v64, v166, v64
	v_exp_f32_e32 v170, v65
	v_sub_f32_e32 v65, v74, v130
	v_add_f32_e32 v64, v167, v64
	v_exp_f32_e32 v171, v65
	v_sub_f32_e32 v65, v75, v130
	v_add_f32_e32 v64, v168, v64
	v_exp_f32_e32 v172, v65
	v_sub_f32_e32 v65, v76, v130
	v_add_f32_e32 v64, v169, v64
	v_exp_f32_e32 v173, v65
	v_sub_f32_e32 v65, v77, v130
	v_add_f32_e32 v64, v170, v64
	v_exp_f32_e32 v174, v65
	v_sub_f32_e32 v65, v78, v130
	v_add_f32_e32 v64, v171, v64
	v_exp_f32_e32 v175, v65
	v_sub_f32_e32 v65, v79, v130
	v_add_f32_e32 v64, v172, v64
	v_exp_f32_e32 v176, v65
	v_sub_f32_e32 v48, v48, v130
	v_add_f32_e32 v64, v173, v64
	v_exp_f32_e32 v177, v48
	v_sub_f32_e32 v48, v49, v130
	v_add_f32_e32 v64, v174, v64
	v_exp_f32_e32 v178, v48
	v_sub_f32_e32 v48, v50, v130
	v_add_f32_e32 v64, v175, v64
	v_exp_f32_e32 v179, v48
	v_sub_f32_e32 v49, v51, v130
	v_add_f32_e32 v48, v176, v64
	v_exp_f32_e32 v180, v49
	v_sub_f32_e32 v49, v52, v130
	v_add_f32_e32 v48, v177, v48
	v_exp_f32_e32 v181, v49
	v_sub_f32_e32 v49, v53, v130
	v_add_f32_e32 v48, v178, v48
	v_exp_f32_e32 v182, v49
	v_sub_f32_e32 v49, v54, v130
	v_add_f32_e32 v48, v179, v48
	v_exp_f32_e32 v183, v49
	v_sub_f32_e32 v49, v55, v130
	v_add_f32_e32 v48, v180, v48
	v_exp_f32_e32 v184, v49
	v_sub_f32_e32 v49, v56, v130
	v_add_f32_e32 v48, v181, v48
	v_exp_f32_e32 v185, v49
	v_sub_f32_e32 v49, v57, v130
	v_add_f32_e32 v48, v182, v48
	v_exp_f32_e32 v186, v49
	v_sub_f32_e32 v49, v58, v130
	v_add_f32_e32 v48, v183, v48
	v_exp_f32_e32 v187, v49
	v_sub_f32_e32 v49, v59, v130
	v_add_f32_e32 v48, v184, v48
	v_exp_f32_e32 v188, v49
	v_sub_f32_e32 v49, v60, v130
	v_add_f32_e32 v48, v185, v48
	v_exp_f32_e32 v189, v49
	v_sub_f32_e32 v49, v61, v130
	v_add_f32_e32 v48, v186, v48
	v_exp_f32_e32 v190, v49
	v_sub_f32_e32 v49, v62, v130
	v_add_f32_e32 v48, v187, v48
	v_exp_f32_e32 v191, v49
	v_sub_f32_e32 v49, v63, v130
	v_add_f32_e32 v48, v188, v48
	v_exp_f32_e32 v192, v49
	v_sub_f32_e32 v32, v32, v130
	v_add_f32_e32 v48, v189, v48
	v_exp_f32_e32 v193, v32
	v_sub_f32_e32 v32, v33, v130
	v_add_f32_e32 v48, v190, v48
	v_exp_f32_e32 v194, v32
	v_sub_f32_e32 v32, v34, v130
	v_add_f32_e32 v48, v191, v48
	v_exp_f32_e32 v195, v32
	v_sub_f32_e32 v33, v35, v130
	v_add_f32_e32 v32, v192, v48
	v_exp_f32_e32 v196, v33
	v_sub_f32_e32 v33, v36, v130
	v_add_f32_e32 v32, v193, v32
	v_exp_f32_e32 v197, v33
	v_sub_f32_e32 v33, v37, v130
	v_add_f32_e32 v32, v194, v32
	v_exp_f32_e32 v198, v33
	v_sub_f32_e32 v33, v38, v130
	v_add_f32_e32 v32, v195, v32
	v_exp_f32_e32 v199, v33
	v_add_f32_e32 v32, v196, v32
	v_add_f32_e32 v32, v197, v32
	v_add_f32_e32 v32, v198, v32
	v_add_f32_e32 v38, v199, v32
	v_sub_f32_e32 v32, v39, v130
	v_cvt_pk_bf16_f32 v34, v112, v113
	v_add_u32_e32 v33, 0x9000, v164
	v_exp_f32_e32 v112, v32
	v_add_u32_e32 v32, 0x9000, v165
	v_cvt_pk_bf16_f32 v35, v114, v115
	v_cvt_pk_bf16_f32 v36, v116, v117
	v_cvt_pk_bf16_f32 v37, v118, v119
	ds_read2_b64 v[48:51], v33 offset1:2
	ds_read2_b64 v[52:55], v32 offset1:2
	v_sub_f32_e32 v39, v40, v130
	v_exp_f32_e32 v113, v39
	s_waitcnt lgkmcnt(1)
	v_mfma_f32_32x32x16_bf16 v[64:79], v[48:51], v[34:37], 0
	v_cvt_pk_bf16_f32 v80, v120, v121
	v_cvt_pk_bf16_f32 v81, v122, v123
	v_cvt_pk_bf16_f32 v82, v124, v125
	v_cvt_pk_bf16_f32 v83, v126, v127
	ds_read2_b64 v[84:87], v33 offset0:4 offset1:6
	v_sub_f32_e32 v16, v16, v130
	v_sub_f32_e32 v17, v17, v130
	s_waitcnt lgkmcnt(1)
	v_mfma_f32_32x32x16_bf16 v[48:63], v[52:55], v[34:37], 0
	v_add_f32_e32 v34, v112, v38
	v_add_f32_e32 v38, v113, v34
	v_sub_f32_e32 v34, v41, v130
	v_exp_f32_e32 v114, v34
	v_sub_f32_e32 v34, v42, v130
	v_exp_f32_e32 v115, v34
	ds_read2_b64 v[34:37], v32 offset0:4 offset1:6
	v_add_f32_e32 v38, v114, v38
	s_waitcnt lgkmcnt(0)
	v_mfma_f32_32x32x16_bf16 v[48:63], v[34:37], v[80:83], v[48:63]
	v_sub_f32_e32 v34, v43, v130
	v_add_f32_e32 v116, v115, v38
	v_cvt_pk_bf16_f32 v38, v96, v97
	v_exp_f32_e32 v96, v34
	v_sub_f32_e32 v34, v44, v130
	v_exp_f32_e32 v97, v34
	v_sub_f32_e32 v34, v45, v130
	v_cvt_pk_bf16_f32 v39, v98, v99
	v_cvt_pk_bf16_f32 v40, v100, v101
	v_cvt_pk_bf16_f32 v41, v102, v103
	v_exp_f32_e32 v98, v34
	ds_read2_b64 v[34:37], v32 offset0:8 offset1:10
	v_mfma_f32_32x32x16_bf16 v[64:79], v[84:87], v[80:83], v[64:79]
	ds_read2_b64 v[84:87], v33 offset0:8 offset1:10
	v_sub_f32_e32 v42, v46, v130
	v_exp_f32_e32 v46, v42
	v_cvt_pk_bf16_f32 v42, v104, v105
	v_cvt_pk_bf16_f32 v43, v106, v107
	v_cvt_pk_bf16_f32 v44, v108, v109
	v_cvt_pk_bf16_f32 v45, v110, v111
	s_waitcnt lgkmcnt(1)
	v_mfma_f32_32x32x16_bf16 v[48:63], v[34:37], v[38:41], v[48:63]
	v_add_f32_e32 v34, v96, v116
	v_add_f32_e32 v34, v97, v34
	ds_read2_b64 v[80:83], v33 offset0:12 offset1:14
	v_add_f32_e32 v34, v98, v34
	v_sub_f32_e32 v0, v0, v130
	v_sub_f32_e32 v1, v1, v130
	s_waitcnt lgkmcnt(1)
	v_mfma_f32_32x32x16_bf16 v[64:79], v[84:87], v[38:41], v[64:79]
	v_add_f32_e32 v84, v46, v34
	v_sub_f32_e32 v34, v47, v130
	v_exp_f32_e32 v47, v34
	ds_read2_b64 v[34:37], v32 offset0:12 offset1:14
	v_cvt_pk_bf16_f32 v38, v132, v133
	v_cvt_pk_bf16_f32 v39, v134, v131
	v_cvt_pk_bf16_f32 v40, v135, v136
	s_waitcnt lgkmcnt(1)
	v_mfma_f32_32x32x16_bf16 v[64:79], v[80:83], v[42:45], v[64:79]
	v_cvt_pk_bf16_f32 v41, v137, v138
	ds_read2_b64 v[80:83], v33 offset0:16 offset1:18
	v_exp_f32_e32 v85, v16
	v_add_f32_e32 v16, v47, v84
	v_exp_f32_e32 v84, v17
	v_sub_f32_e32 v17, v18, v130
	v_exp_f32_e32 v86, v17
	s_waitcnt lgkmcnt(1)
	v_mfma_f32_32x32x16_bf16 v[48:63], v[34:37], v[42:45], v[48:63]
	ds_read2_b64 v[34:37], v32 offset0:16 offset1:18
	v_add_f32_e32 v16, v85, v16
	v_add_f32_e32 v16, v84, v16
	v_add_f32_e32 v87, v86, v16
	v_sub_f32_e32 v16, v19, v130
	v_cvt_pk_bf16_f32 v42, v88, v89
	v_exp_f32_e32 v88, v16
	v_sub_f32_e32 v16, v20, v130
	s_waitcnt lgkmcnt(1)
	v_mfma_f32_32x32x16_bf16 v[64:79], v[80:83], v[38:41], v[64:79]
	v_cvt_pk_bf16_f32 v43, v90, v91
	v_cvt_pk_bf16_f32 v44, v92, v93
	v_cvt_pk_bf16_f32 v45, v94, v95
	ds_read2_b64 v[80:83], v33 offset0:20 offset1:22
	v_exp_f32_e32 v89, v16
	v_sub_f32_e32 v16, v21, v130
	v_exp_f32_e32 v90, v16
	ds_read2_b64 v[16:19], v32 offset0:20 offset1:22
	s_waitcnt lgkmcnt(2)
	v_mfma_f32_32x32x16_bf16 v[48:63], v[34:37], v[38:41], v[48:63]
	v_sub_f32_e32 v20, v22, v130
	v_cvt_pk_bf16_f32 v34, v139, v147
	v_cvt_pk_bf16_f32 v35, v149, v151
	v_cvt_pk_bf16_f32 v36, v153, v166
	v_cvt_pk_bf16_f32 v37, v167, v168
	ds_read2_b64 v[38:41], v33 offset0:24 offset1:26
	v_mov_b32_e32 v147, v141
	s_waitcnt lgkmcnt(2)
	v_mfma_f32_32x32x16_bf16 v[64:79], v[80:83], v[42:45], v[64:79]
	v_exp_f32_e32 v80, v20
	v_sub_f32_e32 v20, v24, v130
	v_mov_b32_e32 v149, v141
	v_mov_b32_e32 v151, v141
	v_mov_b32_e32 v153, v141
	s_waitcnt lgkmcnt(1)
	v_mfma_f32_32x32x16_bf16 v[48:63], v[16:19], v[42:45], v[48:63]
	v_add_f32_e32 v16, v88, v87
	v_add_f32_e32 v16, v89, v16
	v_add_f32_e32 v16, v90, v16
	v_add_f32_e32 v42, v80, v16
	v_sub_f32_e32 v16, v23, v130
	v_exp_f32_e32 v43, v16
	ds_read2_b64 v[16:19], v32 offset0:24 offset1:26
	v_exp_f32_e32 v44, v20
	s_waitcnt lgkmcnt(0)
	v_mfma_f32_32x32x16_bf16 v[48:63], v[16:19], v[34:37], v[48:63]
	v_add_f32_e32 v16, v43, v42
	v_add_f32_e32 v24, v44, v16
	v_sub_f32_e32 v16, v25, v130
	v_exp_f32_e32 v42, v16
	v_sub_f32_e32 v16, v26, v130
	v_cvt_pk_bf16_f32 v20, v169, v170
	v_cvt_pk_bf16_f32 v21, v171, v172
	v_cvt_pk_bf16_f32 v22, v173, v174
	v_cvt_pk_bf16_f32 v23, v175, v176
	v_exp_f32_e32 v45, v16
	ds_read2_b64 v[16:19], v32 offset0:28 offset1:30
	v_mfma_f32_32x32x16_bf16 v[64:79], v[38:41], v[34:37], v[64:79]
	ds_read2_b64 v[38:41], v33 offset0:28 offset1:30
	v_cvt_pk_bf16_f32 v34, v177, v178
	v_cvt_pk_bf16_f32 v35, v179, v180
	v_cvt_pk_bf16_f32 v36, v181, v182
	v_cvt_pk_bf16_f32 v37, v183, v184
	v_add_f32_e32 v24, v42, v24
	v_add_f32_e32 v81, v45, v24
	s_waitcnt lgkmcnt(1)
	v_mfma_f32_32x32x16_bf16 v[48:63], v[16:19], v[20:23], v[48:63]
	v_sub_f32_e32 v16, v27, v130
	v_exp_f32_e32 v82, v16
	v_sub_f32_e32 v16, v28, v130
	v_exp_f32_e32 v83, v16
	v_sub_f32_e32 v16, v29, v130
	v_exp_f32_e32 v87, v16
	ds_read2_b64 v[16:19], v32 offset0:32 offset1:34
	s_waitcnt lgkmcnt(1)
	v_mfma_f32_32x32x16_bf16 v[64:79], v[38:41], v[20:23], v[64:79]
	ds_read2_b64 v[38:41], v33 offset0:32 offset1:34
	v_sub_f32_e32 v20, v30, v130
	s_waitcnt lgkmcnt(0)
	v_mfma_f32_32x32x16_bf16 v[64:79], v[38:41], v[34:37], v[64:79]
	v_exp_f32_e32 v38, v20
	v_cvt_pk_bf16_f32 v20, v185, v186
	v_cvt_pk_bf16_f32 v21, v187, v188
	v_cvt_pk_bf16_f32 v22, v189, v190
	v_cvt_pk_bf16_f32 v23, v191, v192
	ds_read2_b64 v[24:27], v33 offset0:36 offset1:38
	v_mfma_f32_32x32x16_bf16 v[48:63], v[16:19], v[34:37], v[48:63]
	v_add_f32_e32 v16, v82, v81
	v_add_f32_e32 v16, v83, v16
	v_add_f32_e32 v16, v87, v16
	v_add_f32_e32 v34, v38, v16
	v_sub_f32_e32 v16, v31, v130
	v_exp_f32_e32 v35, v16
	ds_read2_b64 v[16:19], v32 offset0:36 offset1:38
	s_waitcnt lgkmcnt(1)
	v_mfma_f32_32x32x16_bf16 v[64:79], v[24:27], v[20:23], v[64:79]
	v_cvt_pk_bf16_f32 v24, v193, v194
	v_cvt_pk_bf16_f32 v25, v195, v196
	v_cvt_pk_bf16_f32 v26, v197, v198
	v_cvt_pk_bf16_f32 v27, v199, v112
	ds_read2_b64 v[28:31], v33 offset0:40 offset1:42
	v_exp_f32_e32 v36, v0
	v_add_f32_e32 v0, v35, v34
	s_waitcnt lgkmcnt(1)
	v_mfma_f32_32x32x16_bf16 v[48:63], v[16:19], v[20:23], v[48:63]
	v_exp_f32_e32 v34, v1
	v_sub_f32_e32 v1, v2, v130
	ds_read2_b64 v[16:19], v32 offset0:40 offset1:42
	v_exp_f32_e32 v37, v1
	v_add_f32_e32 v0, v36, v0
	v_add_f32_e32 v0, v34, v0
	v_cvt_pk_bf16_f32 v20, v113, v114
	v_add_f32_e32 v39, v37, v0
	v_sub_f32_e32 v0, v3, v130
	v_exp_f32_e32 v40, v0
	v_sub_f32_e32 v0, v4, v130
	s_waitcnt lgkmcnt(1)
	v_mfma_f32_32x32x16_bf16 v[64:79], v[28:31], v[24:27], v[64:79]
	v_cvt_pk_bf16_f32 v21, v115, v96
	v_cvt_pk_bf16_f32 v22, v97, v98
	v_cvt_pk_bf16_f32 v23, v46, v47
	ds_read2_b64 v[28:31], v33 offset0:44 offset1:46
	v_exp_f32_e32 v41, v0
	v_sub_f32_e32 v0, v5, v130
	v_exp_f32_e32 v46, v0
	ds_read2_b64 v[0:3], v32 offset0:44 offset1:46
	s_waitcnt lgkmcnt(2)
	v_mfma_f32_32x32x16_bf16 v[48:63], v[16:19], v[24:27], v[48:63]
	v_sub_f32_e32 v4, v6, v130
	v_cvt_pk_bf16_f32 v16, v85, v84
	v_cvt_pk_bf16_f32 v17, v86, v88
	v_cvt_pk_bf16_f32 v18, v89, v90
	v_cvt_pk_bf16_f32 v19, v80, v43
	ds_read2_b64 v[24:27], v33 offset0:48 offset1:50
	s_waitcnt lgkmcnt(2)
	v_mfma_f32_32x32x16_bf16 v[64:79], v[28:31], v[20:23], v[64:79]
	v_exp_f32_e32 v28, v4
	v_sub_f32_e32 v4, v8, v130
	v_sub_f32_e32 v8, v11, v130
	s_waitcnt lgkmcnt(1)
	v_mfma_f32_32x32x16_bf16 v[48:63], v[0:3], v[20:23], v[48:63]
	v_add_f32_e32 v0, v40, v39
	v_add_f32_e32 v0, v41, v0
	v_add_f32_e32 v0, v46, v0
	v_add_f32_e32 v29, v28, v0
	v_sub_f32_e32 v0, v7, v130
	v_exp_f32_e32 v30, v0
	ds_read2_b64 v[0:3], v32 offset0:48 offset1:50
	s_waitcnt lgkmcnt(1)
	v_mfma_f32_32x32x16_bf16 v[64:79], v[24:27], v[16:19], v[64:79]
	v_exp_f32_e32 v24, v4
	v_cvt_pk_bf16_f32 v4, v44, v42
	v_cvt_pk_bf16_f32 v5, v45, v82
	v_cvt_pk_bf16_f32 v6, v83, v87
	v_cvt_pk_bf16_f32 v7, v38, v35
	ds_read2_b64 v[20:23], v33 offset0:52 offset1:54
	s_waitcnt lgkmcnt(1)
	v_mfma_f32_32x32x16_bf16 v[48:63], v[0:3], v[16:19], v[48:63]
	v_add_f32_e32 v0, v30, v29
	v_add_f32_e32 v25, v24, v0
	v_sub_f32_e32 v0, v9, v130
	v_exp_f32_e32 v26, v0
	v_sub_f32_e32 v0, v10, v130
	v_exp_f32_e32 v27, v0
	ds_read2_b64 v[0:3], v32 offset0:52 offset1:54
	s_waitcnt lgkmcnt(0)
	v_mfma_f32_32x32x16_bf16 v[48:63], v[0:3], v[4:7], v[48:63]
	v_sub_f32_e32 v0, v12, v130
	v_mfma_f32_32x32x16_bf16 v[64:79], v[20:23], v[4:7], v[64:79]
	v_exp_f32_e32 v21, v0
	v_sub_f32_e32 v0, v13, v130
	v_exp_f32_e32 v22, v0
	v_sub_f32_e32 v0, v14, v130
	v_exp_f32_e32 v20, v8
	v_cvt_pk_bf16_f32 v8, v36, v34
	v_cvt_pk_bf16_f32 v9, v37, v40
	v_cvt_pk_bf16_f32 v10, v41, v46
	v_cvt_pk_bf16_f32 v11, v28, v30
	v_exp_f32_e32 v23, v0
	ds_read2_b64 v[0:3], v32 offset0:56 offset1:58
	ds_read2_b64 v[16:19], v33 offset0:56 offset1:58
	s_waitcnt lgkmcnt(1)
	v_mfma_f32_32x32x16_bf16 v[48:63], v[0:3], v[8:11], v[48:63]
	v_add_f32_e32 v0, v26, v25
	v_add_f32_e32 v0, v27, v0
	v_add_f32_e32 v0, v20, v0
	v_add_f32_e32 v0, v21, v0
	v_sub_f32_e32 v4, v15, v130
	v_add_f32_e32 v0, v22, v0
	s_waitcnt lgkmcnt(0)
	v_mfma_f32_32x32x16_bf16 v[64:79], v[16:19], v[8:11], v[64:79]
	v_exp_f32_e32 v16, v4
	v_cvt_pk_bf16_f32 v4, v24, v26
	v_cvt_pk_bf16_f32 v5, v27, v20
	v_cvt_pk_bf16_f32 v6, v21, v22
	v_cvt_pk_bf16_f32 v7, v23, v16
	v_add_f32_e32 v8, v23, v0
	ds_read2_b64 v[0:3], v32 offset0:60 offset1:62
	ds_read2_b64 v[12:15], v33 offset0:60 offset1:62
	s_waitcnt lgkmcnt(1)
	v_mfma_f32_32x32x16_bf16 v[48:63], v[0:3], v[4:7], v[48:63]
	v_lshl_add_u64 v[0:1], v[128:129], 0, v[146:147]
	v_add_f32_e32 v10, v16, v8
	ds_bpermute_b32 v11, v155, v10
	v_lshl_add_u64 v[8:9], s[16:17], 0, v[140:141]
	v_lshl_add_u64 v[8:9], v[8:9], 0, s[4:5]
	s_waitcnt lgkmcnt(0)
	v_add_f32_e32 v10, v10, v11
	v_mfma_f32_32x32x16_bf16 v[64:79], v[12:15], v[4:7], v[64:79]
	v_lshl_add_u64 v[4:5], v[0:1], 0, v[148:149]
	global_load_dwordx4 v[0:3], v[4:5], off
	global_load_dwordx4 v[136:139], v[4:5], off offset:32
	global_load_dwordx4 v[132:135], v[4:5], off offset:64
	global_load_dwordx4 v[128:131], v[4:5], off offset:96
	v_div_scale_f32 v6, s[16:17], v10, v10, 1.0
	v_rcp_f32_e32 v7, v6
	s_nop 0
	v_fma_f32 v4, -v6, v7, 1.0
	v_fmac_f32_e32 v7, v4, v7
	v_div_scale_f32 v4, vcc, 1.0, v10, 1.0
	v_mul_f32_e32 v5, v4, v7
	v_fma_f32 v11, -v6, v5, v4
	v_fmac_f32_e32 v5, v11, v7
	v_fma_f32 v4, -v6, v5, v4
	v_div_fmas_f32 v4, v4, v7, v5
	v_div_fixup_f32 v10, v4, v10, 1.0
	v_lshl_add_u64 v[4:5], v[8:9], 0, v[150:151]
	v_lshl_add_u64 v[4:5], v[4:5], 0, v[152:153]
	v_lshl_add_u64 v[6:7], v[4:5], 0, s[12:13]
	v_mul_f32_e32 v8, v64, v10
	v_mul_f32_e32 v9, v65, v10
	v_add_co_u32_e32 v4, vcc, s25, v4
	v_cvt_pk_bf16_f32 v8, v8, v9
	v_mul_f32_e32 v9, v66, v10
	s_nop 0
	v_addc_co_u32_e32 v5, vcc, 0, v5, vcc
	v_mul_f32_e32 v11, v67, v10
	v_cvt_pk_bf16_f32 v9, v9, v11
	global_store_dwordx2 v[4:5], v[8:9], off offset:1536 sc1
	v_mul_f32_e32 v4, v68, v10
	v_mul_f32_e32 v5, v69, v10
	v_cvt_pk_bf16_f32 v4, v4, v5
	v_mul_f32_e32 v5, v70, v10
	v_mul_f32_e32 v8, v71, v10
	v_cvt_pk_bf16_f32 v5, v5, v8
	global_store_dwordx2 v[6:7], v[4:5], off offset:16 sc1
	v_mul_f32_e32 v4, v72, v10
	v_mul_f32_e32 v5, v73, v10
	v_cvt_pk_bf16_f32 v4, v4, v5
	v_mul_f32_e32 v5, v74, v10
	v_mul_f32_e32 v8, v75, v10
	v_cvt_pk_bf16_f32 v5, v5, v8
	global_store_dwordx2 v[6:7], v[4:5], off offset:32 sc1
	v_mul_f32_e32 v4, v76, v10
	v_mul_f32_e32 v5, v77, v10
	v_cvt_pk_bf16_f32 v4, v4, v5
	v_mul_f32_e32 v5, v78, v10
	v_mul_f32_e32 v8, v79, v10
	v_cvt_pk_bf16_f32 v5, v5, v8
	global_store_dwordx2 v[6:7], v[4:5], off offset:48 sc1
	v_mul_f32_e32 v4, v48, v10
	v_mul_f32_e32 v5, v49, v10
	v_cvt_pk_bf16_f32 v4, v4, v5
	v_mul_f32_e32 v5, v50, v10
	v_mul_f32_e32 v8, v51, v10
	v_cvt_pk_bf16_f32 v5, v5, v8
	global_store_dwordx2 v[6:7], v[4:5], off offset:64 sc1
	v_mul_f32_e32 v4, v52, v10
	v_mul_f32_e32 v5, v53, v10
	v_cvt_pk_bf16_f32 v4, v4, v5
	v_mul_f32_e32 v5, v54, v10
	v_mul_f32_e32 v8, v55, v10
	v_cvt_pk_bf16_f32 v5, v5, v8
	global_store_dwordx2 v[6:7], v[4:5], off offset:80 sc1
	v_mul_f32_e32 v4, v56, v10
	v_mul_f32_e32 v5, v57, v10
	v_cvt_pk_bf16_f32 v4, v4, v5
	v_mul_f32_e32 v5, v58, v10
	v_mul_f32_e32 v8, v59, v10
	v_cvt_pk_bf16_f32 v5, v5, v8
	global_store_dwordx2 v[6:7], v[4:5], off offset:96 sc1
	v_mul_f32_e32 v4, v60, v10
	v_mul_f32_e32 v5, v61, v10
	v_cvt_pk_bf16_f32 v4, v4, v5
	v_mul_f32_e32 v5, v62, v10
	s_and_b64 vcc, s[14:15], exec
	v_mul_f32_e32 v8, v63, v10
	v_cvt_pk_bf16_f32 v5, v5, v8
	global_store_dwordx2 v[6:7], v[4:5], off offset:112 sc1
	s_barrier
	s_cbranch_vccnz .LBB0_490

.LBB0_528:
	s_andn2_saveexec_b64 s[10:11], s[10:11]
	s_cbranch_execz .LBB0_548
	s_mov_b64 s[10:11], exec
	s_waitcnt lgkmcnt(0)
	s_waitcnt vmcnt(0)
	v_add_u32_e32 v5, 1, v6
	v_mul_lo_u32 v5, v5, v0
	s_mov_b64 s[98:99], exec
	s_mov_b64 exec, 0xffff
	v_mbcnt_lo_u32_b32 v2, -1, 0
	v_lshlrev_b32_e32 v2, 8, v2
	v_add_u32_e32 v2, 0x2400, v2
	v_mov_b32_e32 v3, 1
	global_atomic_add v2, v3, s[6:7]
	s_mov_b64 exec, s[98:99]
	s_add_u32 s12, s8, 0x2400
	s_addc_u32 s13, s9, 0
	s_mov_b64 s[14:15], 0
	v_mov_b64_e32 v[0:1], s[12:13]
	s_mov_b64 s[10:11], exec
	v_mov_b32_e32 v0, 0
	global_load_dword v1, v0, s[12:13] sc1
	s_mov_b64 s[18:19], 0
	s_waitcnt vmcnt(0)
	v_cmp_lt_u32_e32 vcc, v1, v5
	s_and_saveexec_b64 s[16:17], vcc
	s_cbranch_execz .LBB0_542
	s_add_u32 s14, s6, 0x200
	s_addc_u32 s15, s7, 0
	s_mov_b32 s3, 1
	s_mov_b64 s[6:7], 0
	s_branch .LBB0_535

.LBB0_705:
	s_waitcnt vmcnt(11)
	v_and_b32_e32 v99, 0xffff0000, v33
	v_and_b32_e32 v98, 0xffff0000, v32
	v_lshlrev_b32_e32 v97, 16, v33
	v_lshlrev_b32_e32 v96, 16, v32
	v_pk_mul_f32 v[84:85], v[98:99], v[98:99]
	s_waitcnt lgkmcnt(0)
	global_load_dwordx4 v[80:83], v[40:41], off
	v_pk_fma_f32 v[84:85], v[96:97], v[96:97], v[84:85]
	s_waitcnt vmcnt(11)
	v_and_b32_e32 v105, 0xffff0000, v35
	v_and_b32_e32 v104, 0xffff0000, v34
	v_pk_add_f32 v[100:101], v[84:85], v[84:85] op_sel_hi:[0,1]
	v_lshlrev_b32_e32 v103, 16, v35
	global_load_dwordx4 v[84:87], v[40:41], off offset:1024
	v_lshlrev_b32_e32 v102, 16, v34
	v_pk_mul_f32 v[92:93], v[104:105], v[104:105]
	global_load_dwordx4 v[88:91], v[40:41], off offset:2048
	v_pk_fma_f32 v[92:93], v[102:103], v[102:103], v[92:93]
	s_waitcnt vmcnt(12)
	v_lshlrev_b32_e32 v108, 16, v36
	v_pk_add_f32 v[106:107], v[92:93], v[92:93] op_sel_hi:[0,1]
	global_load_dwordx4 v[92:95], v[40:41], off offset:3072
	v_and_b32_e32 v109, 0xffff0000, v36
	v_lshlrev_b32_e32 v114, 16, v37
	s_waitcnt vmcnt(12)
	v_lshlrev_b32_e32 v110, 16, v38
	v_mul_f32_e32 v111, v108, v108
	v_mul_f32_e32 v113, v109, v109
	v_and_b32_e32 v115, 0xffff0000, v37
	v_mul_f32_e32 v100, v114, v114
	v_mov_b32_e32 v112, v110
	v_pk_fma_f32 v[116:117], v[114:115], v[114:115], v[100:101] op_sel_hi:[1,1,0]
	v_and_b32_e32 v132, 0xffff0000, v38
	v_lshlrev_b32_e32 v118, 16, v39
	v_and_b32_e32 v119, 0xffff0000, v39
	v_pk_add_f32 v[112:113], v[110:111], v[112:113]
	v_mul_f32_e32 v116, v132, v132
	v_mul_f32_e32 v100, v118, v118
	v_mul_f32_e32 v106, v119, v119
	v_mul_f32_e32 v120, v110, v110
	v_mov_b32_e32 v121, v113
	v_pk_add_f32 v[112:113], v[120:121], v[116:117]
	v_pk_add_f32 v[100:101], v[100:101], v[106:107]
	v_mov_b32_e32 v128, v96
	v_pk_add_f32 v[100:101], v[112:113], v[100:101]
	v_mov_b32_e32 v129, v98
	v_add_f32_e32 v100, v100, v101
	ds_bpermute_b32 v101, v18, v100
	v_mov_b32_e32 v98, v97
	v_mov_b32_e32 v131, v104
	v_mov_b32_e32 v104, v103
	v_and_b32_e32 v117, 0xffff0000, v27
	s_waitcnt lgkmcnt(0)
	v_add_f32_e32 v106, v100, v101
	ds_bpermute_b32 v107, v74, v106
	v_lshlrev_b32_e32 v100, 16, v24
	v_and_b32_e32 v101, 0xffff0000, v24
	v_lshlrev_b32_e32 v120, 16, v28
	v_and_b32_e32 v121, 0xffff0000, v28
	s_waitcnt lgkmcnt(0)
	v_add_f32_e32 v111, v106, v107
	ds_bpermute_b32 v116, v75, v111
	v_lshlrev_b32_e32 v106, 16, v25
	v_and_b32_e32 v107, 0xffff0000, v25
	v_and_b32_e32 v127, 0xffff0000, v31
	v_lshlrev_b32_e32 v112, 16, v26
	s_waitcnt lgkmcnt(0)
	v_add_f32_e32 v111, v111, v116
	ds_bpermute_b32 v122, v76, v111
	v_lshlrev_b32_e32 v116, 16, v27
	v_and_b32_e32 v113, 0xffff0000, v26
	v_lshlrev_b32_e32 v124, 16, v30
	v_and_b32_e32 v125, 0xffff0000, v30
	s_waitcnt lgkmcnt(0)
	v_add_f32_e32 v111, v111, v122
	ds_bpermute_b32 v126, v77, v111
	v_lshlrev_b32_e32 v122, 16, v29
	v_and_b32_e32 v123, 0xffff0000, v29
	s_ashr_i32 s13, s12, 31
	s_lshl_b64 s[20:21], s[12:13], 11
	s_waitcnt lgkmcnt(0)
	v_add_f32_e32 v111, v111, v126
	ds_bpermute_b32 v130, v78, v111
	v_lshlrev_b32_e32 v126, 16, v31
	s_waitcnt lgkmcnt(0)
	v_add_f32_e32 v96, v111, v130
	v_fmamk_f32 v96, v96, 0x3a800000, v79
	v_rsq_f32_e32 v96, v96
	v_mov_b32_e32 v130, v102
	v_mov_b32_e32 v111, v132
	v_pk_mul_f32 v[98:99], v[96:97], v[98:99] op_sel_hi:[0,1]
	s_waitcnt vmcnt(3)
	v_pk_fma_f32 v[82:83], v[82:83], v[98:99], v[106:107]
	v_pk_mul_f32 v[98:99], v[96:97], v[104:105] op_sel_hi:[0,1]
	v_pk_mul_f32 v[128:129], v[96:97], v[128:129] op_sel_hi:[0,1]
	v_pk_mul_f32 v[130:131], v[96:97], v[130:131] op_sel_hi:[0,1]
	v_pk_fma_f32 v[80:81], v[80:81], v[128:129], v[100:101]
	v_pk_mul_f32 v[100:101], v[114:115], v[96:97] op_sel_hi:[1,0]
	s_waitcnt vmcnt(2)
	v_pk_fma_f32 v[86:87], v[86:87], v[98:99], v[116:117]
	v_pk_mul_f32 v[98:99], v[108:109], v[96:97] op_sel_hi:[1,0]
	v_pk_fma_f32 v[84:85], v[84:85], v[130:131], v[112:113]
	s_waitcnt vmcnt(1)
	v_pk_fma_f32 v[88:89], v[88:89], v[98:99], v[120:121]
	v_pk_mul_f32 v[98:99], v[110:111], v[96:97] op_sel_hi:[1,0]
	v_pk_mul_f32 v[96:97], v[118:119], v[96:97] op_sel_hi:[1,0]
	v_pk_fma_f32 v[90:91], v[90:91], v[100:101], v[122:123]
	s_waitcnt vmcnt(0)
	v_pk_fma_f32 v[94:95], v[94:95], v[96:97], v[126:127]
	v_mul_f32_e32 v96, v81, v81
	v_mul_f32_e32 v97, v83, v83
	v_fmac_f32_e32 v96, v80, v80
	v_fmac_f32_e32 v97, v82, v82
	v_pk_fma_f32 v[92:93], v[92:93], v[98:99], v[124:125]
	v_add_f32_e32 v96, v96, v97
	v_mul_f32_e32 v97, v85, v85
	v_mul_f32_e32 v98, v87, v87
	v_fmac_f32_e32 v97, v84, v84
	v_fmac_f32_e32 v98, v86, v86
	v_add_f32_e32 v97, v97, v98
	v_add_f32_e32 v96, v96, v97
	v_mul_f32_e32 v97, v89, v89
	v_mul_f32_e32 v98, v91, v91
	v_fmac_f32_e32 v97, v88, v88
	v_fmac_f32_e32 v98, v90, v90
	v_add_f32_e32 v97, v97, v98
	v_add_f32_e32 v96, v97, v96
	v_mul_f32_e32 v97, v93, v93
	v_mul_f32_e32 v98, v95, v95
	v_fmac_f32_e32 v97, v92, v92
	v_fmac_f32_e32 v98, v94, v94
	v_add_f32_e32 v97, v97, v98
	v_add_f32_e32 v96, v97, v96
	ds_bpermute_b32 v97, v18, v96
	v_cvt_pk_bf16_f32 v80, v80, v81
	v_cvt_pk_bf16_f32 v81, v82, v83
	s_waitcnt lgkmcnt(0)
	v_add_f32_e32 v96, v96, v97
	ds_bpermute_b32 v97, v74, v96
	s_waitcnt lgkmcnt(0)
	v_add_f32_e32 v98, v96, v97
	ds_bpermute_b32 v99, v75, v98
	v_lshl_add_u64 v[96:97], v[42:43], 0, s[20:21]
	global_store_dwordx2 v[96:97], v[80:81], off sc1
	v_cvt_pk_bf16_f32 v80, v84, v85
	v_cvt_pk_bf16_f32 v81, v86, v87
	s_waitcnt lgkmcnt(0)
	v_add_f32_e32 v98, v98, v99
	ds_bpermute_b32 v99, v76, v98
	global_store_dwordx2 v[96:97], v[80:81], off offset:512 sc1
	v_cvt_pk_bf16_f32 v82, v88, v89
	v_cvt_pk_bf16_f32 v83, v90, v91
	global_store_dwordx2 v[96:97], v[82:83], off offset:1024 sc1
	s_waitcnt lgkmcnt(0)
	v_add_f32_e32 v84, v98, v99
	ds_bpermute_b32 v85, v77, v84
	v_cvt_pk_bf16_f32 v82, v92, v93
	v_cvt_pk_bf16_f32 v83, v94, v95
	global_store_dwordx2 v[96:97], v[82:83], off offset:1536 sc1
	s_waitcnt lgkmcnt(0)
	v_add_f32_e32 v80, v84, v85
	ds_bpermute_b32 v81, v78, v80
	s_and_saveexec_b64 s[20:21], s[4:5]
	s_cbranch_execz .LBB0_707
	s_waitcnt lgkmcnt(0)
	v_add_f32_e32 v80, v80, v81
	v_fmamk_f32 v80, v80, 0x3a800000, v79
	v_rsq_f32_e32 v80, v80
	s_lshl_b64 s[28:29], s[12:13], 2
	s_add_u32 s28, s22, s28
	s_addc_u32 s29, s23, s29
	global_store_dword v19, v80, s[28:29] sc1
.LBB0_707:
	s_or_b64 exec, exec, s[20:21]
	v_and_b32_e32 v99, 0xffff0000, v53
	v_and_b32_e32 v98, 0xffff0000, v52
	v_lshlrev_b32_e32 v97, 16, v53
	v_lshlrev_b32_e32 v96, 16, v52
	v_pk_mul_f32 v[84:85], v[98:99], v[98:99]
	s_waitcnt lgkmcnt(0)
	global_load_dwordx4 v[80:83], v[40:41], off
	v_pk_fma_f32 v[84:85], v[96:97], v[96:97], v[84:85]
	v_and_b32_e32 v105, 0xffff0000, v55
	v_and_b32_e32 v104, 0xffff0000, v54
	v_pk_add_f32 v[100:101], v[84:85], v[84:85] op_sel_hi:[0,1]
	v_lshlrev_b32_e32 v103, 16, v55
	global_load_dwordx4 v[84:87], v[40:41], off offset:1024
	v_lshlrev_b32_e32 v102, 16, v54
	v_pk_mul_f32 v[92:93], v[104:105], v[104:105]
	global_load_dwordx4 v[88:91], v[40:41], off offset:2048
	v_pk_fma_f32 v[92:93], v[102:103], v[102:103], v[92:93]
	v_lshlrev_b32_e32 v108, 16, v56
	v_pk_add_f32 v[106:107], v[92:93], v[92:93] op_sel_hi:[0,1]
	global_load_dwordx4 v[92:95], v[40:41], off offset:3072
	v_and_b32_e32 v109, 0xffff0000, v56
	v_lshlrev_b32_e32 v114, 16, v57
	v_lshlrev_b32_e32 v110, 16, v58
	v_mul_f32_e32 v111, v108, v108
	v_mul_f32_e32 v113, v109, v109
	v_and_b32_e32 v115, 0xffff0000, v57
	v_mul_f32_e32 v100, v114, v114
	v_mov_b32_e32 v112, v110
	v_pk_fma_f32 v[116:117], v[114:115], v[114:115], v[100:101] op_sel_hi:[1,1,0]
	v_and_b32_e32 v132, 0xffff0000, v58
	v_lshlrev_b32_e32 v118, 16, v59
	v_and_b32_e32 v119, 0xffff0000, v59
	v_pk_add_f32 v[112:113], v[110:111], v[112:113]
	v_mul_f32_e32 v116, v132, v132
	v_mul_f32_e32 v100, v118, v118
	v_mul_f32_e32 v106, v119, v119
	v_mul_f32_e32 v120, v110, v110
	v_mov_b32_e32 v121, v113
	v_pk_add_f32 v[112:113], v[120:121], v[116:117]
	v_pk_add_f32 v[100:101], v[100:101], v[106:107]
	v_mov_b32_e32 v128, v96
	v_pk_add_f32 v[100:101], v[112:113], v[100:101]
	v_mov_b32_e32 v129, v98
	v_add_f32_e32 v100, v100, v101
	ds_bpermute_b32 v101, v18, v100
	v_mov_b32_e32 v98, v97
	v_mov_b32_e32 v131, v104
	v_mov_b32_e32 v104, v103
	v_and_b32_e32 v117, 0xffff0000, v47
	s_waitcnt lgkmcnt(0)
	v_add_f32_e32 v106, v100, v101
	ds_bpermute_b32 v107, v74, v106
	v_lshlrev_b32_e32 v100, 16, v44
	v_and_b32_e32 v101, 0xffff0000, v44
	v_lshlrev_b32_e32 v120, 16, v48
	v_and_b32_e32 v121, 0xffff0000, v48
	s_waitcnt lgkmcnt(0)
	v_add_f32_e32 v111, v106, v107
	ds_bpermute_b32 v116, v75, v111
	v_lshlrev_b32_e32 v106, 16, v45
	v_and_b32_e32 v107, 0xffff0000, v45
	v_and_b32_e32 v127, 0xffff0000, v51
	v_lshlrev_b32_e32 v112, 16, v46
	s_waitcnt lgkmcnt(0)
	v_add_f32_e32 v111, v111, v116
	ds_bpermute_b32 v122, v76, v111
	v_lshlrev_b32_e32 v116, 16, v47
	v_and_b32_e32 v113, 0xffff0000, v46
	v_lshlrev_b32_e32 v124, 16, v50
	v_and_b32_e32 v125, 0xffff0000, v50
	s_waitcnt lgkmcnt(0)
	v_add_f32_e32 v111, v111, v122
	ds_bpermute_b32 v126, v77, v111
	v_lshlrev_b32_e32 v122, 16, v49
	v_and_b32_e32 v123, 0xffff0000, v49
	s_ashr_i32 s7, s6, 31
	s_lshl_b64 s[20:21], s[6:7], 11
	s_waitcnt lgkmcnt(0)
	v_add_f32_e32 v111, v111, v126
	ds_bpermute_b32 v130, v78, v111
	v_lshlrev_b32_e32 v126, 16, v51
	s_waitcnt lgkmcnt(0)
	v_add_f32_e32 v96, v111, v130
	v_fmamk_f32 v96, v96, 0x3a800000, v79
	v_rsq_f32_e32 v96, v96
	v_mov_b32_e32 v130, v102
	v_mov_b32_e32 v111, v132
	v_pk_mul_f32 v[98:99], v[96:97], v[98:99] op_sel_hi:[0,1]
	s_waitcnt vmcnt(3)
	v_pk_fma_f32 v[82:83], v[82:83], v[98:99], v[106:107]
	v_pk_mul_f32 v[98:99], v[96:97], v[104:105] op_sel_hi:[0,1]
	v_pk_mul_f32 v[128:129], v[96:97], v[128:129] op_sel_hi:[0,1]
	v_pk_mul_f32 v[130:131], v[96:97], v[130:131] op_sel_hi:[0,1]
	v_pk_fma_f32 v[80:81], v[80:81], v[128:129], v[100:101]
	v_pk_mul_f32 v[100:101], v[114:115], v[96:97] op_sel_hi:[1,0]
	s_waitcnt vmcnt(2)
	v_pk_fma_f32 v[86:87], v[86:87], v[98:99], v[116:117]
	v_pk_mul_f32 v[98:99], v[108:109], v[96:97] op_sel_hi:[1,0]
	v_pk_fma_f32 v[84:85], v[84:85], v[130:131], v[112:113]
	s_waitcnt vmcnt(1)
	v_pk_fma_f32 v[88:89], v[88:89], v[98:99], v[120:121]
	v_pk_mul_f32 v[98:99], v[110:111], v[96:97] op_sel_hi:[1,0]
	v_pk_mul_f32 v[96:97], v[118:119], v[96:97] op_sel_hi:[1,0]
	v_pk_fma_f32 v[90:91], v[90:91], v[100:101], v[122:123]
	s_waitcnt vmcnt(0)
	v_pk_fma_f32 v[94:95], v[94:95], v[96:97], v[126:127]
	v_mul_f32_e32 v96, v81, v81
	v_mul_f32_e32 v97, v83, v83
	v_fmac_f32_e32 v96, v80, v80
	v_fmac_f32_e32 v97, v82, v82
	v_pk_fma_f32 v[92:93], v[92:93], v[98:99], v[124:125]
	v_add_f32_e32 v96, v96, v97
	v_mul_f32_e32 v97, v85, v85
	v_mul_f32_e32 v98, v87, v87
	v_fmac_f32_e32 v97, v84, v84
	v_fmac_f32_e32 v98, v86, v86
	v_add_f32_e32 v97, v97, v98
	v_add_f32_e32 v96, v96, v97
	v_mul_f32_e32 v97, v89, v89
	v_mul_f32_e32 v98, v91, v91
	v_fmac_f32_e32 v97, v88, v88
	v_fmac_f32_e32 v98, v90, v90
	v_add_f32_e32 v97, v97, v98
	v_add_f32_e32 v96, v97, v96
	v_mul_f32_e32 v97, v93, v93
	v_mul_f32_e32 v98, v95, v95
	v_fmac_f32_e32 v97, v92, v92
	v_fmac_f32_e32 v98, v94, v94
	v_add_f32_e32 v97, v97, v98
	v_add_f32_e32 v96, v97, v96
	ds_bpermute_b32 v97, v18, v96
	v_cvt_pk_bf16_f32 v80, v80, v81
	v_cvt_pk_bf16_f32 v81, v82, v83
	s_waitcnt lgkmcnt(0)
	v_add_f32_e32 v96, v96, v97
	ds_bpermute_b32 v97, v74, v96
	s_waitcnt lgkmcnt(0)
	v_add_f32_e32 v98, v96, v97
	ds_bpermute_b32 v99, v75, v98
	v_lshl_add_u64 v[96:97], v[42:43], 0, s[20:21]
	global_store_dwordx2 v[96:97], v[80:81], off sc1
	v_cvt_pk_bf16_f32 v80, v84, v85
	v_cvt_pk_bf16_f32 v81, v86, v87
	s_waitcnt lgkmcnt(0)
	v_add_f32_e32 v98, v98, v99
	ds_bpermute_b32 v99, v76, v98
	global_store_dwordx2 v[96:97], v[80:81], off offset:512 sc1
	v_cvt_pk_bf16_f32 v82, v88, v89
	v_cvt_pk_bf16_f32 v83, v90, v91
	global_store_dwordx2 v[96:97], v[82:83], off offset:1024 sc1
	s_waitcnt lgkmcnt(0)
	v_add_f32_e32 v84, v98, v99
	ds_bpermute_b32 v85, v77, v84
	v_cvt_pk_bf16_f32 v82, v92, v93
	v_cvt_pk_bf16_f32 v83, v94, v95
	global_store_dwordx2 v[96:97], v[82:83], off offset:1536 sc1
	s_waitcnt lgkmcnt(0)
	v_add_f32_e32 v80, v84, v85
	ds_bpermute_b32 v81, v78, v80
	s_and_saveexec_b64 s[20:21], s[4:5]
	s_cbranch_execnz .LBB0_710
	s_or_b64 exec, exec, s[20:21]
	s_add_i32 s20, s24, s16
	s_cmpk_gt_i32 s20, 0x7fff
	s_cbranch_scc0 .LBB0_711

.LBB0_710:
	s_waitcnt lgkmcnt(0)
	v_add_f32_e32 v80, v80, v81
	v_fmamk_f32 v80, v80, 0x3a800000, v79
	v_rsq_f32_e32 v80, v80
	s_lshl_b64 s[28:29], s[6:7], 2
	s_add_u32 s28, s22, s28
	s_addc_u32 s29, s23, s29
	global_store_dword v19, v80, s[28:29] sc1
	s_or_b64 exec, exec, s[20:21]
	s_add_i32 s20, s24, s16
	s_cmpk_gt_i32 s20, 0x7fff
	s_cbranch_scc1 .LBB0_709

.LBB0_712:
	v_and_b32_e32 v99, 0xffff0000, v17
	v_and_b32_e32 v98, 0xffff0000, v16
	v_lshlrev_b32_e32 v97, 16, v17
	v_lshlrev_b32_e32 v96, 16, v16
	v_pk_mul_f32 v[84:85], v[98:99], v[98:99]
	s_waitcnt lgkmcnt(0)
	global_load_dwordx4 v[80:83], v[40:41], off
	v_pk_fma_f32 v[84:85], v[96:97], v[96:97], v[84:85]
	v_and_b32_e32 v105, 0xffff0000, v61
	v_and_b32_e32 v104, 0xffff0000, v60
	v_pk_add_f32 v[100:101], v[84:85], v[84:85] op_sel_hi:[0,1]
	v_lshlrev_b32_e32 v103, 16, v61
	global_load_dwordx4 v[84:87], v[40:41], off offset:1024
	v_lshlrev_b32_e32 v102, 16, v60
	v_pk_mul_f32 v[92:93], v[104:105], v[104:105]
	global_load_dwordx4 v[88:91], v[40:41], off offset:2048
	v_pk_fma_f32 v[92:93], v[102:103], v[102:103], v[92:93]
	v_lshlrev_b32_e32 v108, 16, v62
	v_pk_add_f32 v[106:107], v[92:93], v[92:93] op_sel_hi:[0,1]
	global_load_dwordx4 v[92:95], v[40:41], off offset:3072
	v_and_b32_e32 v109, 0xffff0000, v62
	v_lshlrev_b32_e32 v114, 16, v63
	v_lshlrev_b32_e32 v110, 16, v64
	v_mul_f32_e32 v111, v108, v108
	v_mul_f32_e32 v113, v109, v109
	v_and_b32_e32 v115, 0xffff0000, v63
	v_mul_f32_e32 v100, v114, v114
	v_mov_b32_e32 v112, v110
	v_pk_fma_f32 v[116:117], v[114:115], v[114:115], v[100:101] op_sel_hi:[1,1,0]
	v_and_b32_e32 v132, 0xffff0000, v64
	v_lshlrev_b32_e32 v118, 16, v65
	v_and_b32_e32 v119, 0xffff0000, v65
	v_pk_add_f32 v[112:113], v[110:111], v[112:113]
	v_mul_f32_e32 v116, v132, v132
	v_mul_f32_e32 v106, v118, v118
	v_mul_f32_e32 v100, v119, v119
	v_mul_f32_e32 v120, v110, v110
	v_mov_b32_e32 v121, v113
	v_pk_add_f32 v[112:113], v[120:121], v[116:117]
	v_pk_add_f32 v[100:101], v[106:107], v[100:101]
	v_mov_b32_e32 v128, v96
	v_pk_add_f32 v[100:101], v[112:113], v[100:101]
	v_mov_b32_e32 v129, v98
	v_add_f32_e32 v100, v100, v101
	ds_bpermute_b32 v101, v18, v100
	v_mov_b32_e32 v98, v97
	v_mov_b32_e32 v131, v104
	v_mov_b32_e32 v104, v103
	v_and_b32_e32 v117, 0xffff0000, v3
	s_waitcnt lgkmcnt(0)
	v_add_f32_e32 v106, v100, v101
	ds_bpermute_b32 v107, v74, v106
	v_lshlrev_b32_e32 v100, 16, v0
	v_and_b32_e32 v101, 0xffff0000, v0
	v_lshlrev_b32_e32 v120, 16, v4
	v_and_b32_e32 v121, 0xffff0000, v4
	s_waitcnt lgkmcnt(0)
	v_add_f32_e32 v111, v106, v107
	ds_bpermute_b32 v116, v75, v111
	v_lshlrev_b32_e32 v106, 16, v1
	v_and_b32_e32 v107, 0xffff0000, v1
	v_and_b32_e32 v127, 0xffff0000, v7
	v_lshlrev_b32_e32 v112, 16, v2
	s_waitcnt lgkmcnt(0)
	v_add_f32_e32 v111, v111, v116
	ds_bpermute_b32 v122, v76, v111
	v_lshlrev_b32_e32 v116, 16, v3
	v_and_b32_e32 v113, 0xffff0000, v2
	v_lshlrev_b32_e32 v124, 16, v6
	v_and_b32_e32 v125, 0xffff0000, v6
	s_waitcnt lgkmcnt(0)
	v_add_f32_e32 v111, v111, v122
	ds_bpermute_b32 v126, v77, v111
	v_lshlrev_b32_e32 v122, 16, v5
	v_and_b32_e32 v123, 0xffff0000, v5
	s_ashr_i32 s11, s10, 31
	s_lshl_b64 s[16:17], s[10:11], 11
	s_waitcnt lgkmcnt(0)
	v_add_f32_e32 v111, v111, v126
	ds_bpermute_b32 v130, v78, v111
	v_lshlrev_b32_e32 v126, 16, v7
	s_waitcnt lgkmcnt(0)
	v_add_f32_e32 v96, v111, v130
	v_fmamk_f32 v96, v96, 0x3a800000, v79
	v_rsq_f32_e32 v96, v96
	v_mov_b32_e32 v130, v102
	v_mov_b32_e32 v111, v132
	v_pk_mul_f32 v[98:99], v[96:97], v[98:99] op_sel_hi:[0,1]
	s_waitcnt vmcnt(3)
	v_pk_fma_f32 v[82:83], v[82:83], v[98:99], v[106:107]
	v_pk_mul_f32 v[98:99], v[96:97], v[104:105] op_sel_hi:[0,1]
	v_pk_mul_f32 v[128:129], v[96:97], v[128:129] op_sel_hi:[0,1]
	v_pk_mul_f32 v[130:131], v[96:97], v[130:131] op_sel_hi:[0,1]
	v_pk_fma_f32 v[80:81], v[80:81], v[128:129], v[100:101]
	v_pk_mul_f32 v[100:101], v[114:115], v[96:97] op_sel_hi:[1,0]
	s_waitcnt vmcnt(2)
	v_pk_fma_f32 v[86:87], v[86:87], v[98:99], v[116:117]
	v_pk_mul_f32 v[98:99], v[108:109], v[96:97] op_sel_hi:[1,0]
	v_pk_fma_f32 v[84:85], v[84:85], v[130:131], v[112:113]
	s_waitcnt vmcnt(1)
	v_pk_fma_f32 v[88:89], v[88:89], v[98:99], v[120:121]
	v_pk_mul_f32 v[98:99], v[110:111], v[96:97] op_sel_hi:[1,0]
	v_pk_mul_f32 v[96:97], v[118:119], v[96:97] op_sel_hi:[1,0]
	v_pk_fma_f32 v[90:91], v[90:91], v[100:101], v[122:123]
	s_waitcnt vmcnt(0)
	v_pk_fma_f32 v[94:95], v[94:95], v[96:97], v[126:127]
	v_mul_f32_e32 v96, v81, v81
	v_mul_f32_e32 v97, v83, v83
	v_fmac_f32_e32 v96, v80, v80
	v_fmac_f32_e32 v97, v82, v82
	v_pk_fma_f32 v[92:93], v[92:93], v[98:99], v[124:125]
	v_add_f32_e32 v96, v96, v97
	v_mul_f32_e32 v97, v85, v85
	v_mul_f32_e32 v98, v87, v87
	v_fmac_f32_e32 v97, v84, v84
	v_fmac_f32_e32 v98, v86, v86
	v_add_f32_e32 v97, v97, v98
	v_add_f32_e32 v96, v96, v97
	v_mul_f32_e32 v97, v89, v89
	v_mul_f32_e32 v98, v91, v91
	v_fmac_f32_e32 v97, v88, v88
	v_fmac_f32_e32 v98, v90, v90
	v_add_f32_e32 v97, v97, v98
	v_add_f32_e32 v96, v97, v96
	v_mul_f32_e32 v97, v93, v93
	v_mul_f32_e32 v98, v95, v95
	v_fmac_f32_e32 v97, v92, v92
	v_fmac_f32_e32 v98, v94, v94
	v_add_f32_e32 v97, v97, v98
	v_add_f32_e32 v96, v97, v96
	ds_bpermute_b32 v97, v18, v96
	v_cvt_pk_bf16_f32 v80, v80, v81
	v_cvt_pk_bf16_f32 v81, v82, v83
	s_waitcnt lgkmcnt(0)
	v_add_f32_e32 v96, v96, v97
	ds_bpermute_b32 v97, v74, v96
	s_waitcnt lgkmcnt(0)
	v_add_f32_e32 v98, v96, v97
	ds_bpermute_b32 v99, v75, v98
	v_lshl_add_u64 v[96:97], v[42:43], 0, s[16:17]
	global_store_dwordx2 v[96:97], v[80:81], off sc1
	v_cvt_pk_bf16_f32 v80, v84, v85
	v_cvt_pk_bf16_f32 v81, v86, v87
	s_waitcnt lgkmcnt(0)
	v_add_f32_e32 v98, v98, v99
	ds_bpermute_b32 v99, v76, v98
	global_store_dwordx2 v[96:97], v[80:81], off offset:512 sc1
	v_cvt_pk_bf16_f32 v82, v88, v89
	v_cvt_pk_bf16_f32 v83, v90, v91
	global_store_dwordx2 v[96:97], v[82:83], off offset:1024 sc1
	s_waitcnt lgkmcnt(0)
	v_add_f32_e32 v84, v98, v99
	ds_bpermute_b32 v85, v77, v84
	v_cvt_pk_bf16_f32 v82, v92, v93
	v_cvt_pk_bf16_f32 v83, v94, v95
	global_store_dwordx2 v[96:97], v[82:83], off offset:1536 sc1
	s_waitcnt lgkmcnt(0)
	v_add_f32_e32 v80, v84, v85
	ds_bpermute_b32 v81, v78, v80
	s_and_saveexec_b64 s[16:17], s[4:5]
	s_cbranch_execz .LBB0_714
	s_waitcnt lgkmcnt(0)
	v_add_f32_e32 v80, v80, v81
	v_fmamk_f32 v80, v80, 0x3a800000, v79
	v_rsq_f32_e32 v80, v80
	s_lshl_b64 s[18:19], s[10:11], 2
	s_add_u32 s18, s22, s18
	s_addc_u32 s19, s23, s19
	global_store_dword v19, v80, s[18:19] sc1
.LBB0_714:
	s_or_b64 exec, exec, s[16:17]
	v_and_b32_e32 v99, 0xffff0000, v67
	v_and_b32_e32 v98, 0xffff0000, v66
	v_lshlrev_b32_e32 v97, 16, v67
	v_lshlrev_b32_e32 v96, 16, v66
	v_pk_mul_f32 v[84:85], v[98:99], v[98:99]
	s_waitcnt lgkmcnt(0)
	global_load_dwordx4 v[80:83], v[40:41], off
	v_pk_fma_f32 v[84:85], v[96:97], v[96:97], v[84:85]
	v_and_b32_e32 v105, 0xffff0000, v69
	v_and_b32_e32 v104, 0xffff0000, v68
	v_pk_add_f32 v[100:101], v[84:85], v[84:85] op_sel_hi:[0,1]
	v_lshlrev_b32_e32 v103, 16, v69
	global_load_dwordx4 v[84:87], v[40:41], off offset:1024
	v_lshlrev_b32_e32 v102, 16, v68
	v_pk_mul_f32 v[92:93], v[104:105], v[104:105]
	global_load_dwordx4 v[88:91], v[40:41], off offset:2048
	v_pk_fma_f32 v[92:93], v[102:103], v[102:103], v[92:93]
	v_lshlrev_b32_e32 v108, 16, v70
	v_pk_add_f32 v[106:107], v[92:93], v[92:93] op_sel_hi:[0,1]
	global_load_dwordx4 v[92:95], v[40:41], off offset:3072
	v_and_b32_e32 v109, 0xffff0000, v70
	v_lshlrev_b32_e32 v114, 16, v71
	v_lshlrev_b32_e32 v110, 16, v72
	v_mul_f32_e32 v111, v108, v108
	v_mul_f32_e32 v113, v109, v109
	v_and_b32_e32 v115, 0xffff0000, v71
	v_mul_f32_e32 v100, v114, v114
	v_mov_b32_e32 v112, v110
	v_pk_fma_f32 v[116:117], v[114:115], v[114:115], v[100:101] op_sel_hi:[1,1,0]
	v_and_b32_e32 v132, 0xffff0000, v72
	v_lshlrev_b32_e32 v118, 16, v73
	v_and_b32_e32 v119, 0xffff0000, v73
	v_pk_add_f32 v[112:113], v[110:111], v[112:113]
	v_mul_f32_e32 v116, v132, v132
	v_mul_f32_e32 v106, v118, v118
	v_mul_f32_e32 v100, v119, v119
	v_mul_f32_e32 v120, v110, v110
	v_mov_b32_e32 v121, v113
	v_pk_add_f32 v[112:113], v[120:121], v[116:117]
	v_pk_add_f32 v[100:101], v[106:107], v[100:101]
	v_mov_b32_e32 v128, v96
	v_pk_add_f32 v[100:101], v[112:113], v[100:101]
	v_mov_b32_e32 v129, v98
	v_add_f32_e32 v100, v100, v101
	ds_bpermute_b32 v101, v18, v100
	v_mov_b32_e32 v98, v97
	v_mov_b32_e32 v131, v104
	v_mov_b32_e32 v104, v103
	v_and_b32_e32 v117, 0xffff0000, v11
	s_waitcnt lgkmcnt(0)
	v_add_f32_e32 v106, v100, v101
	ds_bpermute_b32 v107, v74, v106
	v_lshlrev_b32_e32 v100, 16, v8
	v_and_b32_e32 v101, 0xffff0000, v8
	v_lshlrev_b32_e32 v120, 16, v12
	v_and_b32_e32 v121, 0xffff0000, v12
	s_waitcnt lgkmcnt(0)
	v_add_f32_e32 v111, v106, v107
	ds_bpermute_b32 v116, v75, v111
	v_lshlrev_b32_e32 v106, 16, v9
	v_and_b32_e32 v107, 0xffff0000, v9
	v_and_b32_e32 v127, 0xffff0000, v15
	v_lshlrev_b32_e32 v112, 16, v10
	s_waitcnt lgkmcnt(0)
	v_add_f32_e32 v111, v111, v116
	ds_bpermute_b32 v122, v76, v111
	v_lshlrev_b32_e32 v116, 16, v11
	v_and_b32_e32 v113, 0xffff0000, v10
	v_lshlrev_b32_e32 v124, 16, v14
	v_and_b32_e32 v125, 0xffff0000, v14
	s_waitcnt lgkmcnt(0)
	v_add_f32_e32 v111, v111, v122
	ds_bpermute_b32 v126, v77, v111
	v_lshlrev_b32_e32 v122, 16, v13
	v_and_b32_e32 v123, 0xffff0000, v13
	s_ashr_i32 s9, s8, 31
	s_lshl_b64 s[16:17], s[8:9], 11
	s_waitcnt lgkmcnt(0)
	v_add_f32_e32 v111, v111, v126
	ds_bpermute_b32 v130, v78, v111
	v_lshlrev_b32_e32 v126, 16, v15
	s_waitcnt lgkmcnt(0)
	v_add_f32_e32 v96, v111, v130
	v_fmamk_f32 v96, v96, 0x3a800000, v79
	v_rsq_f32_e32 v96, v96
	v_mov_b32_e32 v130, v102
	v_mov_b32_e32 v111, v132
	v_pk_mul_f32 v[98:99], v[96:97], v[98:99] op_sel_hi:[0,1]
	s_waitcnt vmcnt(3)
	v_pk_fma_f32 v[82:83], v[82:83], v[98:99], v[106:107]
	v_pk_mul_f32 v[98:99], v[96:97], v[104:105] op_sel_hi:[0,1]
	v_pk_mul_f32 v[128:129], v[96:97], v[128:129] op_sel_hi:[0,1]
	v_pk_mul_f32 v[130:131], v[96:97], v[130:131] op_sel_hi:[0,1]
	v_pk_fma_f32 v[80:81], v[80:81], v[128:129], v[100:101]
	v_pk_mul_f32 v[100:101], v[114:115], v[96:97] op_sel_hi:[1,0]
	s_waitcnt vmcnt(2)
	v_pk_fma_f32 v[86:87], v[86:87], v[98:99], v[116:117]
	v_pk_mul_f32 v[98:99], v[108:109], v[96:97] op_sel_hi:[1,0]
	v_pk_fma_f32 v[84:85], v[84:85], v[130:131], v[112:113]
	s_waitcnt vmcnt(1)
	v_pk_fma_f32 v[88:89], v[88:89], v[98:99], v[120:121]
	v_pk_mul_f32 v[98:99], v[110:111], v[96:97] op_sel_hi:[1,0]
	v_pk_mul_f32 v[96:97], v[118:119], v[96:97] op_sel_hi:[1,0]
	v_pk_fma_f32 v[90:91], v[90:91], v[100:101], v[122:123]
	s_waitcnt vmcnt(0)
	v_pk_fma_f32 v[94:95], v[94:95], v[96:97], v[126:127]
	v_mul_f32_e32 v96, v81, v81
	v_mul_f32_e32 v97, v83, v83
	v_fmac_f32_e32 v96, v80, v80
	v_fmac_f32_e32 v97, v82, v82
	v_pk_fma_f32 v[92:93], v[92:93], v[98:99], v[124:125]
	v_add_f32_e32 v96, v96, v97
	v_mul_f32_e32 v97, v85, v85
	v_mul_f32_e32 v98, v87, v87
	v_fmac_f32_e32 v97, v84, v84
	v_fmac_f32_e32 v98, v86, v86
	v_add_f32_e32 v97, v97, v98
	v_add_f32_e32 v96, v96, v97
	v_mul_f32_e32 v97, v89, v89
	v_mul_f32_e32 v98, v91, v91
	v_fmac_f32_e32 v97, v88, v88
	v_fmac_f32_e32 v98, v90, v90
	v_add_f32_e32 v97, v97, v98
	v_add_f32_e32 v96, v97, v96
	v_mul_f32_e32 v97, v93, v93
	v_mul_f32_e32 v98, v95, v95
	v_fmac_f32_e32 v97, v92, v92
	v_fmac_f32_e32 v98, v94, v94
	v_add_f32_e32 v97, v97, v98
	v_add_f32_e32 v96, v97, v96
	ds_bpermute_b32 v97, v18, v96
	v_cvt_pk_bf16_f32 v80, v80, v81
	v_cvt_pk_bf16_f32 v81, v82, v83
	s_waitcnt lgkmcnt(0)
	v_add_f32_e32 v96, v96, v97
	ds_bpermute_b32 v97, v74, v96
	s_waitcnt lgkmcnt(0)
	v_add_f32_e32 v98, v96, v97
	ds_bpermute_b32 v99, v75, v98
	v_lshl_add_u64 v[96:97], v[42:43], 0, s[16:17]
	global_store_dwordx2 v[96:97], v[80:81], off sc1
	v_cvt_pk_bf16_f32 v80, v84, v85
	v_cvt_pk_bf16_f32 v81, v86, v87
	s_waitcnt lgkmcnt(0)
	v_add_f32_e32 v98, v98, v99
	ds_bpermute_b32 v99, v76, v98
	global_store_dwordx2 v[96:97], v[80:81], off offset:512 sc1
	v_cvt_pk_bf16_f32 v82, v88, v89
	v_cvt_pk_bf16_f32 v83, v90, v91
	global_store_dwordx2 v[96:97], v[82:83], off offset:1024 sc1
	s_waitcnt lgkmcnt(0)
	v_add_f32_e32 v84, v98, v99
	ds_bpermute_b32 v85, v77, v84
	v_cvt_pk_bf16_f32 v82, v92, v93
	v_cvt_pk_bf16_f32 v83, v94, v95
	global_store_dwordx2 v[96:97], v[82:83], off offset:1536 sc1
	s_waitcnt lgkmcnt(0)
	v_add_f32_e32 v80, v84, v85
	ds_bpermute_b32 v81, v78, v80
	s_and_saveexec_b64 s[16:17], s[4:5]
	s_cbranch_execz .LBB0_701
	s_waitcnt lgkmcnt(0)
	v_add_f32_e32 v80, v80, v81
	v_fmamk_f32 v80, v80, 0x3a800000, v79
	v_rsq_f32_e32 v80, v80
	s_lshl_b64 s[18:19], s[8:9], 2
	s_add_u32 s18, s22, s18
	s_addc_u32 s19, s23, s19
	global_store_dword v19, v80, s[18:19] sc1
	s_branch .LBB0_701

.LBB0_749:
	s_andn2_saveexec_b64 s[14:15], s[14:15]
	s_cbranch_execz .LBB0_769
	s_mov_b64 s[14:15], exec
	s_waitcnt lgkmcnt(0)
	s_waitcnt vmcnt(0)
	v_add_u32_e32 v5, 1, v6
	v_mul_lo_u32 v5, v5, v0
	s_mov_b64 s[98:99], exec
	s_mov_b64 exec, 0xffff
	v_mbcnt_lo_u32_b32 v2, -1, 0
	v_lshlrev_b32_e32 v2, 8, v2
	v_add_u32_e32 v2, 0x2400, v2
	v_mov_b32_e32 v3, 1
	global_atomic_add v2, v3, s[10:11]
	s_mov_b64 exec, s[98:99]
	s_add_u32 s16, s12, 0x2400
	s_addc_u32 s17, s13, 0
	s_mov_b64 s[18:19], 0
	v_mov_b64_e32 v[0:1], s[16:17]
	s_mov_b64 s[14:15], exec
	v_mov_b32_e32 v0, 0
	global_load_dword v1, v0, s[16:17] sc1
	s_mov_b64 s[22:23], 0
	s_waitcnt vmcnt(0)
	v_cmp_lt_u32_e32 vcc, v1, v5
	s_and_saveexec_b64 s[20:21], vcc
	s_cbranch_execz .LBB0_763
	s_add_u32 s18, s10, 0x200
	s_addc_u32 s19, s11, 0
	s_mov_b32 s3, 1
	s_mov_b64 s[10:11], 0
	s_branch .LBB0_756
